# added: conv-in-proj (P1) epilogue row-rms prefetch; residual-GEMM epilogues (P3,P5,P9) prefetch the bf16 residual 4 steps ahead instead of load-wait-store per step
# speedup vs baseline: 1.0439x; 1.0073x over previous
; #define PG8_STAGE(bufoff, gbase, voff) do { _Pragma("unroll") for (int _i = 0; _i < 2; ++_i) \
;         __builtin_amdgcn_global_load_lds((const unsigned*)((const char*)(gbase) + (voff)[_i]), (PG8_LAS unsigned*)(lds + (bufoff) + ldsw + _i * 8192), 16, 0, 0); } while (0)
; #define PG8_WAIT_V(n) asm volatile("s_waitcnt vmcnt(" #n ")" ::: "memory")
; #define PG8_BAR __builtin_amdgcn_s_barrier()
; template <class Epi, class Sched, bool ALIGN_EPI = false, bool SP2 = false>
; __device__ __forceinline__ void gemm_phase(PG8_LAS unsigned char* lds, const Gemm g, const Sched& S, const Epi& E) {
;     ...
;     const char* cA = (const char*)g.A + (size_t)cur.pm * tstep + (size_t)cur.kt0 * kstep; const char* cB = (const char*)g.Bt + (size_t)cur.pn * tstep + (size_t)cur.kt0 * kstep;
;     S.a_ready(cur);
;     if constexpr (SP2) {
;         PG8_STAGE(PG8_SB(0, 0), cB, voffB); PG8_STAGE(PG8_SB(0, 1), cB + hstep, voffB); PG8_STAGE(PG8_SA(0, 0), cA, voffA); PG8_STAGE(PG8_SA(0, 1), cA + hstep, voffA);
;         if (wr == 1) PG8_BAR;
;         PG8_WAIT_V(2); PG8_BAR;
;         PG8_STAGE(PG8_SB(1, 0), cB + kstep, voffB); PG8_STAGE(PG8_SA(1, 0), cA + kstep, voffA); PG8_STAGE(PG8_SB(1, 1), cB + hstep + kstep, voffB);
;         PG8_WAIT_V(6); PG8_BAR;
; __device__ __forceinline__ float row_rs(const float* part, int row) {
;     const f32x4* p = (const f32x4*)(part + (size_t)row * 16);
;     const f32x4 a = p[0], b = p[1], c = p[2], d = p[3];
.LBB0_155:
	s_andn2_b64 vcc, exec, s[0:1]
	s_cbranch_vccnz .LBB0_235
	v_and_b32_e32 v246, 15, v146
	v_lshrrev_b32_e32 v206, 8, v146
	v_lshl_or_b32 v246, v206, 6, v246
	v_bfe_u32 v206, v146, 4, 2
	v_lshlrev_b32_e32 v206, 4, v206
	v_lshl_or_b32 v246, v246, 6, v206
	v_lshl_add_u32 v206, s2, 14, v246
	v_add_u32_e32 v207, 0x2000, v206
	global_load_dwordx4 v[232:235], v206, s[90:91]
	global_load_dwordx4 v[236:239], v206, s[90:91] offset:1024
	global_load_dwordx4 v[240:243], v206, s[90:91] offset:2048
	global_load_dwordx4 v[248:251], v206, s[90:91] offset:3072
	global_load_dwordx4 v[252:255], v207, s[90:91]
	v_lshrrev_b32_e32 v3, 1, v146
	v_and_b32_e32 v14, 24, v3
	v_lshrrev_b32_e32 v3, 5, v146
	v_and_b32_e32 v3, 4, v3
	v_bfe_u32 v4, v146, 2, 2
	v_lshlrev_b32_e32 v1, 4, v146
	v_and_b32_e32 v2, 32, v146
	v_bfe_u32 v12, v146, 2, 4
	v_or3_b32 v3, v3, v4, v14
	v_lshrrev_b32_e32 v4, 3, v146
	s_movk_i32 s1, 0x70
	v_bitop3_b32 v10, v1, v2, 48 bitop3:0x6c
	v_and_b32_e32 v11, 64, v146
	v_and_or_b32 v5, v4, s1, v12
	s_movk_i32 s1, 0x60
	v_add_u32_e32 v13, 0x2000, v1
	v_or_b32_e32 v2, v10, v11
	v_and_or_b32 v4, v4, s1, v3
	v_lshrrev_b32_e32 v1, 7, v13
	s_movk_i32 s1, 0xf0
	v_lshl_or_b32 v140, v4, 11, v2
	v_and_or_b32 v4, v1, s1, v12
	s_movk_i32 s1, 0xe0
	v_and_or_b32 v1, v1, s1, v3
	s_lshr_b32 s1, s18, 6
	s_ashr_i32 s3, s2, 31
	s_ashr_i32 s5, s4, 31
	s_lshr_b32 s0, s18, 8
	s_lshl_b32 s33, s1, 10
	s_lshl_b64 s[8:9], s[2:3], 19
	s_lshl_b64 s[10:11], s[4:5], 19
	s_add_u32 s34, s74, s10
	s_addc_u32 s35, s75, s11
	s_add_i32 s38, s33, 0
	s_add_i32 m0, s38, 0x10000
	v_lshl_or_b32 v144, v1, 11, v2
	global_load_lds_dwordx4 v140, s[34:35]
	s_add_i32 m0, s38, 0x12000
	s_add_u32 s10, s34, 0x40000
	global_load_lds_dwordx4 v144, s[34:35]
	s_addc_u32 s11, s35, 0
	s_add_i32 m0, s38, 0x14000
	v_lshl_or_b32 v138, v5, 11, v2
	global_load_lds_dwordx4 v140, s[10:11]
	s_add_i32 m0, s38, 0x16000
	s_add_u32 s30, s88, s8
	s_addc_u32 s31, s89, s9
	s_add_i32 s39, s38, 0x2000
	global_load_lds_dwordx4 v144, s[10:11]
	s_mov_b32 m0, s38
	s_add_u32 s8, s30, 0x40000
	v_lshl_or_b32 v142, v4, 11, v2
	global_load_lds_dwordx4 v138, s[30:31]
	s_mov_b32 m0, s39
	s_addc_u32 s9, s31, 0
	s_add_i32 s40, s38, 0x4000
	global_load_lds_dwordx4 v142, s[30:31]
	s_mov_b32 m0, s40
	s_add_i32 s41, s38, 0x6000
	global_load_lds_dwordx4 v138, s[8:9]
	s_mov_b32 m0, s41
	v_mov_b32_e32 v149, 0
	global_load_lds_dwordx4 v142, s[8:9]
	v_mov_b32_e32 v141, v149
	v_mov_b32_e32 v145, v149
	v_mov_b32_e32 v139, v149
	v_mov_b32_e32 v143, v149
	s_cmp_eq_u32 s0, 1
	s_mov_b32 s42, 0
	v_lshl_add_u64 v[8:9], s[34:35], 0, v[140:141]
	s_waitcnt lgkmcnt(0)
	v_lshl_add_u64 v[6:7], s[34:35], 0, v[144:145]
	v_lshl_add_u64 v[2:3], s[30:31], 0, v[138:139]
	s_cselect_b64 s[8:9], -1, 0
	s_cmp_lg_u32 s0, 1
	v_lshl_add_u64 v[4:5], s[30:31], 0, v[142:143]
	s_cbranch_scc1 .LBB0_158
	s_barrier

; __device__ __forceinline__ u32x4 pack8(const f32x4 a, const f32x4 b) { u32x4 w; w.x = cvt_pk_bf16(a[0], a[1]); w.y = cvt_pk_bf16(a[2], a[3]); w.z = cvt_pk_bf16(b[0], b[1]); w.w = cvt_pk_bf16(b[2], b[3]); return w; }
; __device__ __forceinline__ float row_rs(const float* part, int row) {
;     const f32x4* p = (const f32x4*)(part + (size_t)row * 16);
;     const f32x4 a = p[0], b = p[1], c = p[2], d = p[3];
;     const float s = (((a[0] + a[1]) + (a[2] + a[3])) + ((b[0] + b[1]) + (b[2] + b[3]))) + (((c[0] + c[1]) + (c[2] + c[3])) + ((d[0] + d[1]) + (d[2] + d[3])));
;     return rsqrtf(s * (1.0f / D) + RMS_EPS);
; }
;     __device__ __forceinline__ void operator()(const Acc& acc, const pg8::Unit& u, int wr, int wc, int fr, int fq) const {
; #pragma unroll
;         for (int ai = 0; ai < 2; ++ai)
; #pragma unroll
;             for (int m = 0; m < 4; ++m) {
;                 const int row = u.pm * 256 + ai * 128 + wr * 64 + m * 16 + fr;
;                 const float rs = row_rs(part, row);
;                 if (u.pn < 4) {
; #pragma unroll
;                     for (int bj = 0; bj < 2; ++bj) { const int col = u.pn * 256 + bj * 128 + wc * 32 + 8 * fq;
;                         *(u32x4*)(bb + (size_t)row * D + col) = pack8(acc[ai][bj][m][0] * rs, acc[ai][bj][m][1] * rs); }
;                 } else {
;                     const int col = (u.pn - 4) * 128 + wc * 32 + 8 * fq;
;                     const f32x4 u0 = (acc[ai][0][m][0] * rs) * (acc[ai][1][m][0] * rs), u1 = (acc[ai][0][m][1] * rs) * (acc[ai][1][m][1] * rs);
;                     *(u32x4*)(ub + (size_t)row * D + col) = pack8(u0, u1);
.LBB0_167:
	s_waitcnt vmcnt(8)
	v_lshl_add_u32 v206, s2, 14, v246
	v_add_u32_e32 v207, 0x2000, v206
	global_load_dwordx4 v[178:181], v207, s[90:91] offset:1024
	global_load_dwordx4 v[182:185], v207, s[90:91] offset:2048
	global_load_dwordx4 v[186:189], v207, s[90:91] offset:3072
	v_add_f32_e32 v232, v232, v233
	v_add_f32_e32 v234, v234, v235
	v_add_f32_e32 v236, v236, v237
	v_add_f32_e32 v238, v238, v239
	v_add_f32_e32 v240, v240, v241
	v_add_f32_e32 v242, v242, v243
	v_add_f32_e32 v248, v248, v249
	v_add_f32_e32 v250, v250, v251
	v_add_f32_e32 v252, v252, v253
	v_add_f32_e32 v254, v254, v255
	v_add_f32_e32 v190, v232, v234
	v_add_f32_e32 v191, v236, v238
	v_add_f32_e32 v192, v240, v242
	v_add_f32_e32 v193, v248, v250
	v_add_f32_e32 v194, v252, v254
	v_mov_b32_e32 v198, v190
	v_mov_b32_e32 v199, v191
	v_mov_b32_e32 v200, v192
	v_mov_b32_e32 v201, v193
	v_mov_b32_e32 v202, v194
	v_permlane16_swap_b32_e32 v190, v198
	v_permlane16_swap_b32_e32 v191, v199
	v_permlane16_swap_b32_e32 v192, v200
	v_permlane16_swap_b32_e32 v193, v201
	v_permlane16_swap_b32_e32 v194, v202
	v_add_f32_e32 v190, v190, v198
	v_add_f32_e32 v191, v191, v199
	v_add_f32_e32 v192, v192, v200
	v_add_f32_e32 v193, v193, v201
	v_add_f32_e32 v194, v194, v202
	v_mov_b32_e32 v198, v190
	v_mov_b32_e32 v199, v191
	v_mov_b32_e32 v200, v192
	v_mov_b32_e32 v201, v193
	v_mov_b32_e32 v202, v194
	v_permlane32_swap_b32_e32 v190, v198
	v_permlane32_swap_b32_e32 v191, v199
	v_permlane32_swap_b32_e32 v192, v200
	v_permlane32_swap_b32_e32 v193, v201
	v_permlane32_swap_b32_e32 v194, v202
	v_add_f32_e32 v190, v190, v198
	v_add_f32_e32 v191, v191, v199
	v_add_f32_e32 v192, v192, v200
	v_add_f32_e32 v193, v193, v201
	v_add_f32_e32 v194, v194, v202
	v_fmamk_f32 v190, v190, 0x3a800000, v169
	v_fmamk_f32 v191, v191, 0x3a800000, v169
	v_fmamk_f32 v192, v192, 0x3a800000, v169
	v_fmamk_f32 v193, v193, 0x3a800000, v169
	v_fmamk_f32 v194, v194, 0x3a800000, v169
	v_rsq_f32_e32 v190, v190
	v_rsq_f32_e32 v191, v191
	v_rsq_f32_e32 v192, v192
	v_rsq_f32_e32 v193, v193
	v_rsq_f32_e32 v194, v194
	v_lshl_add_u32 v206, s24, 14, v246
	v_add_u32_e32 v207, 0x2000, v206
	global_load_dwordx4 v[232:235], v206, s[90:91]
	global_load_dwordx4 v[236:239], v206, s[90:91] offset:1024
	global_load_dwordx4 v[240:243], v206, s[90:91] offset:2048
	global_load_dwordx4 v[248:251], v206, s[90:91] offset:3072
	global_load_dwordx4 v[252:255], v207, s[90:91]
	s_lshl_b32 s23, s2, 8
	s_add_i32 s23, s23, s45
	v_or_b32_e32 v158, s23, v1
	v_ashrrev_i32_e32 v159, 31, v158
	v_lshlrev_b64 v[130:131], 6, v[158:159]
	v_lshl_add_u64 v[162:163], s[90:91], 0, v[130:131]
	s_cmp_gt_i32 s4, 3
	s_cselect_b64 s[30:31], -1, 0
	s_and_b64 s[2:3], exec, s[30:31]
	s_mov_b64 s[34:35], -1
	v_lshl_add_u32 v148, s4, 7, v164
	v_lshlrev_b64 v[162:163], 11, v[158:159]
	s_nop 0
	s_nop 1
	s_nop 0
	v_mov_b32_e32 v160, v190
	s_mov_b64 vcc, s[2:3]
	s_cbranch_vccz .LBB0_171
	v_pk_mul_f32 v[130:131], v[128:129], v[160:161] op_sel_hi:[1,0]
	v_pk_mul_f32 v[134:135], v[126:127], v[160:161] op_sel_hi:[1,0]
	v_pk_mul_f32 v[132:133], v[120:121], v[160:161] op_sel_hi:[1,0]
	v_pk_mul_f32 v[136:137], v[118:119], v[160:161] op_sel_hi:[1,0]
	v_pk_mul_f32 v[132:133], v[130:131], v[132:133]
	v_pk_mul_f32 v[130:131], v[134:135], v[136:137]
	v_pk_mul_f32 v[134:135], v[124:125], v[160:161] op_sel_hi:[1,0]
	v_pk_mul_f32 v[170:171], v[122:123], v[160:161] op_sel_hi:[1,0]
	v_pk_mul_f32 v[136:137], v[116:117], v[160:161] op_sel_hi:[1,0]
	v_pk_mul_f32 v[172:173], v[114:115], v[160:161] op_sel_hi:[1,0]
	v_pk_mul_f32 v[136:137], v[134:135], v[136:137]
	v_pk_mul_f32 v[134:135], v[170:171], v[172:173]
	v_lshl_add_u64 v[174:175], s[12:13], 0, v[162:163]
	v_cmp_lt_i32_e32 vcc, s54, v158
	v_cvt_pk_bf16_f32 v170, v130, v131
	v_cvt_pk_bf16_f32 v171, v132, v133
	v_cvt_pk_bf16_f32 v172, v134, v135
	v_cvt_pk_bf16_f32 v173, v136, v137
	v_lshl_add_u64 v[174:175], v[148:149], 1, v[174:175]
	s_and_b64 s[34:35], vcc, s[20:21]
	global_store_dwordx4 v[174:175], v[170:173], off
	s_and_saveexec_b64 s[2:3], s[34:35]
	s_cbranch_execz .LBB0_170
	v_add_u32_e32 v159, 0xffffc000, v158
	v_lshrrev_b32_e32 v159, 1, v159
	v_and_b32_e32 v159, 0x7fffffe6, v159
	v_add_u32_e32 v170, v159, v165
	v_mov_b32_e32 v171, v149
	v_lshlrev_b64 v[170:171], 12, v[170:171]
	v_lshl_add_u64 v[170:171], s[14:15], 0, v[170:171]
	v_lshl_add_u64 v[170:171], v[148:149], 2, v[170:171]
	global_store_dwordx4 v[170:171], v[130:133], off
	global_store_dwordx4 v[170:171], v[134:137], off offset:16

; __device__ __forceinline__ u32x4 pack8(const f32x4 a, const f32x4 b) { u32x4 w; w.x = cvt_pk_bf16(a[0], a[1]); w.y = cvt_pk_bf16(a[2], a[3]); w.z = cvt_pk_bf16(b[0], b[1]); w.w = cvt_pk_bf16(b[2], b[3]); return w; }
;     __device__ __forceinline__ void operator()(const Acc& acc, const pg8::Unit& u, int wr, int wc, int fr, int fq) const {
;     ...
;             for (int m = 0; m < 4; ++m) {
;                 const int row = u.pm * 256 + ai * 128 + wr * 64 + m * 16 + fr;
;                 const float rs = row_rs(part, row);
;                 if (u.pn < 4) {
; #pragma unroll
;                     for (int bj = 0; bj < 2; ++bj) { const int col = u.pn * 256 + bj * 128 + wc * 32 + 8 * fq;
;                         *(u32x4*)(bb + (size_t)row * D + col) = pack8(acc[ai][bj][m][0] * rs, acc[ai][bj][m][1] * rs); }
;                 } else {
;                     const int col = (u.pn - 4) * 128 + wc * 32 + 8 * fq;
;                     const f32x4 u0 = (acc[ai][0][m][0] * rs) * (acc[ai][1][m][0] * rs), u1 = (acc[ai][0][m][1] * rs) * (acc[ai][1][m][1] * rs);
;                     *(u32x4*)(ub + (size_t)row * D + col) = pack8(u0, u1);
.LBB0_173:
	v_or_b32_e32 v122, 16, v158
	v_ashrrev_i32_e32 v123, 31, v122
	v_lshlrev_b64 v[114:115], 6, v[122:123]
	v_lshl_add_u64 v[128:129], s[90:91], 0, v[114:115]
	s_mov_b64 s[34:35], -1
	s_andn2_b64 vcc, exec, s[30:31]
	v_lshlrev_b64 v[126:127], 11, v[122:123]
	s_nop 0
	s_nop 1
	v_cndmask_b32_e64 v115, 0, 1, s[30:31]
	v_cmp_ne_u32_e64 s[2:3], 1, v115
	v_mov_b32_e32 v124, v191
	s_cbranch_vccnz .LBB0_177
	v_pk_mul_f32 v[114:115], v[112:113], v[124:125] op_sel_hi:[1,0]
	v_pk_mul_f32 v[118:119], v[110:111], v[124:125] op_sel_hi:[1,0]
	v_pk_mul_f32 v[116:117], v[104:105], v[124:125] op_sel_hi:[1,0]
	v_pk_mul_f32 v[120:121], v[102:103], v[124:125] op_sel_hi:[1,0]
	v_pk_mul_f32 v[116:117], v[114:115], v[116:117]
	v_pk_mul_f32 v[114:115], v[118:119], v[120:121]
	v_pk_mul_f32 v[118:119], v[108:109], v[124:125] op_sel_hi:[1,0]
	v_pk_mul_f32 v[128:129], v[106:107], v[124:125] op_sel_hi:[1,0]
	v_pk_mul_f32 v[120:121], v[100:101], v[124:125] op_sel_hi:[1,0]
	v_pk_mul_f32 v[132:133], v[98:99], v[124:125] op_sel_hi:[1,0]
	v_pk_mul_f32 v[120:121], v[118:119], v[120:121]
	v_pk_mul_f32 v[118:119], v[128:129], v[132:133]
	v_lshl_add_u64 v[128:129], s[12:13], 0, v[126:127]
	v_cmp_lt_i32_e32 vcc, s54, v122
	v_cvt_pk_bf16_f32 v132, v114, v115
	v_cvt_pk_bf16_f32 v133, v116, v117
	v_cvt_pk_bf16_f32 v134, v118, v119
	v_cvt_pk_bf16_f32 v135, v120, v121
	v_lshl_add_u64 v[128:129], v[148:149], 1, v[128:129]
	s_and_b64 s[30:31], vcc, s[20:21]
	global_store_dwordx4 v[128:129], v[132:135], off
	s_and_saveexec_b64 s[4:5], s[30:31]
	s_cbranch_execz .LBB0_176
	v_add_u32_e32 v122, 0xffffc010, v158
	v_lshrrev_b32_e32 v122, 1, v122
	v_and_b32_e32 v122, 0x7fffffee, v122
	v_add_u32_e32 v122, v122, v165
	v_mov_b32_e32 v123, v149
	v_lshlrev_b64 v[122:123], 12, v[122:123]
	v_lshl_add_u64 v[122:123], s[14:15], 0, v[122:123]
	v_lshl_add_u64 v[122:123], v[148:149], 2, v[122:123]
	global_store_dwordx4 v[122:123], v[114:117], off
	global_store_dwordx4 v[122:123], v[118:121], off offset:16

; __device__ __forceinline__ u32x4 pack8(const f32x4 a, const f32x4 b) { u32x4 w; w.x = cvt_pk_bf16(a[0], a[1]); w.y = cvt_pk_bf16(a[2], a[3]); w.z = cvt_pk_bf16(b[0], b[1]); w.w = cvt_pk_bf16(b[2], b[3]); return w; }
;     __device__ __forceinline__ void operator()(const Acc& acc, const pg8::Unit& u, int wr, int wc, int fr, int fq) const {
;     ...
;             for (int m = 0; m < 4; ++m) {
;                 const int row = u.pm * 256 + ai * 128 + wr * 64 + m * 16 + fr;
;                 const float rs = row_rs(part, row);
;                 if (u.pn < 4) {
; #pragma unroll
;                     for (int bj = 0; bj < 2; ++bj) { const int col = u.pn * 256 + bj * 128 + wc * 32 + 8 * fq;
;                         *(u32x4*)(bb + (size_t)row * D + col) = pack8(acc[ai][bj][m][0] * rs, acc[ai][bj][m][1] * rs); }
;                 } else {
;                     const int col = (u.pn - 4) * 128 + wc * 32 + 8 * fq;
;                     const f32x4 u0 = (acc[ai][0][m][0] * rs) * (acc[ai][1][m][0] * rs), u1 = (acc[ai][0][m][1] * rs) * (acc[ai][1][m][1] * rs);
;                     *(u32x4*)(ub + (size_t)row * D + col) = pack8(u0, u1);
.LBB0_179:
	v_or_b32_e32 v108, 32, v158
	v_ashrrev_i32_e32 v109, 31, v108
	v_lshlrev_b64 v[98:99], 6, v[108:109]
	v_lshl_add_u64 v[106:107], s[90:91], 0, v[98:99]
	s_mov_b64 s[30:31], -1
	s_and_b64 vcc, exec, s[2:3]
	v_lshlrev_b64 v[110:111], 11, v[108:109]
	s_nop 0
	s_nop 1
	s_nop 0
	v_mov_b32_e32 v106, v192
	s_cbranch_vccnz .LBB0_183
	v_pk_mul_f32 v[98:99], v[96:97], v[106:107] op_sel_hi:[1,0]
	v_pk_mul_f32 v[102:103], v[94:95], v[106:107] op_sel_hi:[1,0]
	v_pk_mul_f32 v[100:101], v[88:89], v[106:107] op_sel_hi:[1,0]
	v_pk_mul_f32 v[104:105], v[86:87], v[106:107] op_sel_hi:[1,0]
	v_pk_mul_f32 v[100:101], v[98:99], v[100:101]
	v_pk_mul_f32 v[98:99], v[102:103], v[104:105]
	v_pk_mul_f32 v[102:103], v[92:93], v[106:107] op_sel_hi:[1,0]
	v_pk_mul_f32 v[112:113], v[90:91], v[106:107] op_sel_hi:[1,0]
	v_pk_mul_f32 v[104:105], v[84:85], v[106:107] op_sel_hi:[1,0]
	v_pk_mul_f32 v[114:115], v[82:83], v[106:107] op_sel_hi:[1,0]
	v_pk_mul_f32 v[104:105], v[102:103], v[104:105]
	v_pk_mul_f32 v[102:103], v[112:113], v[114:115]
	v_lshl_add_u64 v[116:117], s[12:13], 0, v[110:111]
	v_cmp_lt_i32_e32 vcc, s54, v108
	v_cvt_pk_bf16_f32 v112, v98, v99
	v_cvt_pk_bf16_f32 v113, v100, v101
	v_cvt_pk_bf16_f32 v114, v102, v103
	v_cvt_pk_bf16_f32 v115, v104, v105
	v_lshl_add_u64 v[116:117], v[148:149], 1, v[116:117]
	s_and_b64 s[30:31], vcc, s[20:21]
	global_store_dwordx4 v[116:117], v[112:115], off
	s_and_saveexec_b64 s[4:5], s[30:31]
	s_cbranch_execz .LBB0_182
	v_add_u32_e32 v107, 0xffffc020, v158
	v_lshrrev_b32_e32 v107, 1, v107
	v_and_b32_e32 v107, 0x7ffffff6, v107
	v_add_u32_e32 v108, v107, v165
	v_mov_b32_e32 v109, v149
	v_lshlrev_b64 v[108:109], 12, v[108:109]
	v_lshl_add_u64 v[108:109], s[14:15], 0, v[108:109]
	v_lshl_add_u64 v[108:109], v[148:149], 2, v[108:109]
	global_store_dwordx4 v[108:109], v[98:101], off
	global_store_dwordx4 v[108:109], v[102:105], off offset:16

; __device__ __forceinline__ u32x4 pack8(const f32x4 a, const f32x4 b) { u32x4 w; w.x = cvt_pk_bf16(a[0], a[1]); w.y = cvt_pk_bf16(a[2], a[3]); w.z = cvt_pk_bf16(b[0], b[1]); w.w = cvt_pk_bf16(b[2], b[3]); return w; }
;     __device__ __forceinline__ void operator()(const Acc& acc, const pg8::Unit& u, int wr, int wc, int fr, int fq) const {
;     ...
;             for (int m = 0; m < 4; ++m) {
;                 const int row = u.pm * 256 + ai * 128 + wr * 64 + m * 16 + fr;
;                 const float rs = row_rs(part, row);
;                 if (u.pn < 4) {
; #pragma unroll
;                     for (int bj = 0; bj < 2; ++bj) { const int col = u.pn * 256 + bj * 128 + wc * 32 + 8 * fq;
;                         *(u32x4*)(bb + (size_t)row * D + col) = pack8(acc[ai][bj][m][0] * rs, acc[ai][bj][m][1] * rs); }
;                 } else {
;                     const int col = (u.pn - 4) * 128 + wc * 32 + 8 * fq;
;                     const f32x4 u0 = (acc[ai][0][m][0] * rs) * (acc[ai][1][m][0] * rs), u1 = (acc[ai][0][m][1] * rs) * (acc[ai][1][m][1] * rs);
;                     *(u32x4*)(ub + (size_t)row * D + col) = pack8(u0, u1);
;                     float* dst = nullptr;
;                     if (row < TP) { const int l = row & (SEQ - 1); if (l >= SEQ - 2) dst = convp + ((size_t)(row >> 11) * 2 + (l - (SEQ - 2))) * D + col; }
;                     else { const int ts = row - TP, l = ts & 3; if (l >= 2) dst = convs + ((size_t)(ts >> 2) * 2 + (l - 2)) * D + col; }
;                     if (dst) { *(f32x4*)dst = u0; *(f32x4*)(dst + 4) = u1; }
.LBB0_185:
	v_or_b32_e32 v94, 48, v158
	v_ashrrev_i32_e32 v95, 31, v94
	v_lshlrev_b64 v[82:83], 6, v[94:95]
	v_lshl_add_u64 v[96:97], s[90:91], 0, v[82:83]
	s_nop 0
	s_mov_b64 s[30:31], -1
	s_and_b64 vcc, exec, s[2:3]
	v_lshlrev_b64 v[92:93], 11, v[94:95]
	s_nop 0
	s_nop 1
	s_nop 0
	v_mov_b32_e32 v90, v193
	s_cbranch_vccnz .LBB0_191
	v_pk_mul_f32 v[82:83], v[80:81], v[90:91] op_sel_hi:[1,0]
	v_pk_mul_f32 v[86:87], v[78:79], v[90:91] op_sel_hi:[1,0]
	v_pk_mul_f32 v[84:85], v[72:73], v[90:91] op_sel_hi:[1,0]
	v_pk_mul_f32 v[88:89], v[70:71], v[90:91] op_sel_hi:[1,0]
	v_pk_mul_f32 v[84:85], v[82:83], v[84:85]
	v_pk_mul_f32 v[82:83], v[86:87], v[88:89]
	v_pk_mul_f32 v[86:87], v[76:77], v[90:91] op_sel_hi:[1,0]
	v_pk_mul_f32 v[96:97], v[74:75], v[90:91] op_sel_hi:[1,0]
	v_pk_mul_f32 v[88:89], v[68:69], v[90:91] op_sel_hi:[1,0]
	v_pk_mul_f32 v[98:99], v[66:67], v[90:91] op_sel_hi:[1,0]
	v_pk_mul_f32 v[88:89], v[86:87], v[88:89]
	v_pk_mul_f32 v[86:87], v[96:97], v[98:99]
	v_lshl_add_u64 v[100:101], s[12:13], 0, v[92:93]
	v_cvt_pk_bf16_f32 v96, v82, v83
	v_cvt_pk_bf16_f32 v97, v84, v85
	v_cvt_pk_bf16_f32 v98, v86, v87
	v_cvt_pk_bf16_f32 v99, v88, v89
	v_lshl_add_u64 v[100:101], v[148:149], 1, v[100:101]
	v_cmp_lt_i32_e32 vcc, s54, v94
	global_store_dwordx4 v[100:101], v[96:99], off
	s_and_saveexec_b64 s[4:5], vcc
	s_xor_b64 s[4:5], exec, s[4:5]
	s_cbranch_execnz .LBB0_222
	s_andn2_saveexec_b64 s[4:5], s[4:5]
	s_cbranch_execnz .LBB0_225

; __device__ __forceinline__ u32x4 pack8(const f32x4 a, const f32x4 b) { u32x4 w; w.x = cvt_pk_bf16(a[0], a[1]); w.y = cvt_pk_bf16(a[2], a[3]); w.z = cvt_pk_bf16(b[0], b[1]); w.w = cvt_pk_bf16(b[2], b[3]); return w; }
;     __device__ __forceinline__ void operator()(const Acc& acc, const pg8::Unit& u, int wr, int wc, int fr, int fq) const {
;     ...
;             for (int m = 0; m < 4; ++m) {
;                 const int row = u.pm * 256 + ai * 128 + wr * 64 + m * 16 + fr;
;                 const float rs = row_rs(part, row);
;                 if (u.pn < 4) {
; #pragma unroll
;                     for (int bj = 0; bj < 2; ++bj) { const int col = u.pn * 256 + bj * 128 + wc * 32 + 8 * fq;
;                         *(u32x4*)(bb + (size_t)row * D + col) = pack8(acc[ai][bj][m][0] * rs, acc[ai][bj][m][1] * rs); }
;                 } else {
;                     const int col = (u.pn - 4) * 128 + wc * 32 + 8 * fq;
;                     const f32x4 u0 = (acc[ai][0][m][0] * rs) * (acc[ai][1][m][0] * rs), u1 = (acc[ai][0][m][1] * rs) * (acc[ai][1][m][1] * rs);
;                     *(u32x4*)(ub + (size_t)row * D + col) = pack8(u0, u1);
.LBB0_193:
	s_addk_i32 s23, 0x80
	v_or_b32_e32 v74, s23, v1
	v_ashrrev_i32_e32 v75, 31, v74
	v_lshlrev_b64 v[66:67], 6, v[74:75]
	v_lshl_add_u64 v[80:81], s[90:91], 0, v[66:67]
	s_nop 0
	s_mov_b64 s[30:31], -1
	s_and_b64 vcc, exec, s[2:3]
	v_lshlrev_b64 v[78:79], 11, v[74:75]
	s_nop 0
	s_nop 1
	s_nop 0
	v_mov_b32_e32 v76, v194
	s_cbranch_vccnz .LBB0_197
	v_pk_mul_f32 v[66:67], v[64:65], v[76:77] op_sel_hi:[1,0]
	v_pk_mul_f32 v[70:71], v[62:63], v[76:77] op_sel_hi:[1,0]
	v_pk_mul_f32 v[68:69], v[56:57], v[76:77] op_sel_hi:[1,0]
	v_pk_mul_f32 v[72:73], v[54:55], v[76:77] op_sel_hi:[1,0]
	v_pk_mul_f32 v[68:69], v[66:67], v[68:69]
	v_pk_mul_f32 v[66:67], v[70:71], v[72:73]
	v_pk_mul_f32 v[70:71], v[60:61], v[76:77] op_sel_hi:[1,0]
	v_pk_mul_f32 v[80:81], v[58:59], v[76:77] op_sel_hi:[1,0]
	v_pk_mul_f32 v[72:73], v[52:53], v[76:77] op_sel_hi:[1,0]
	v_pk_mul_f32 v[82:83], v[50:51], v[76:77] op_sel_hi:[1,0]
	v_pk_mul_f32 v[72:73], v[70:71], v[72:73]
	v_pk_mul_f32 v[70:71], v[80:81], v[82:83]
	v_lshl_add_u64 v[84:85], s[12:13], 0, v[78:79]
	v_cmp_lt_i32_e32 vcc, s54, v74
	v_cvt_pk_bf16_f32 v80, v66, v67
	v_cvt_pk_bf16_f32 v81, v68, v69
	v_cvt_pk_bf16_f32 v82, v70, v71
	v_cvt_pk_bf16_f32 v83, v72, v73
	v_lshl_add_u64 v[84:85], v[148:149], 1, v[84:85]
	s_and_b64 s[30:31], vcc, s[20:21]
	global_store_dwordx4 v[84:85], v[80:83], off
	s_and_saveexec_b64 s[4:5], s[30:31]
	s_cbranch_execz .LBB0_196
	v_add_u32_e32 v75, 0xffffc000, v74
	v_lshrrev_b32_e32 v75, 1, v75
	v_and_b32_e32 v75, 0x7ffffffe, v75
	v_add_u32_e32 v80, v75, v165
	v_mov_b32_e32 v81, v149
	v_lshlrev_b64 v[80:81], 12, v[80:81]
	v_lshl_add_u64 v[80:81], s[14:15], 0, v[80:81]
	v_lshl_add_u64 v[80:81], v[148:149], 2, v[80:81]
	global_store_dwordx4 v[80:81], v[66:69], off
	global_store_dwordx4 v[80:81], v[70:73], off offset:16

; __device__ __forceinline__ u32x4 pack8(const f32x4 a, const f32x4 b) { u32x4 w; w.x = cvt_pk_bf16(a[0], a[1]); w.y = cvt_pk_bf16(a[2], a[3]); w.z = cvt_pk_bf16(b[0], b[1]); w.w = cvt_pk_bf16(b[2], b[3]); return w; }
; __device__ __forceinline__ float row_rs(const float* part, int row) {
;     const f32x4* p = (const f32x4*)(part + (size_t)row * 16);
;     const f32x4 a = p[0], b = p[1], c = p[2], d = p[3];
;     const float s = (((a[0] + a[1]) + (a[2] + a[3])) + ((b[0] + b[1]) + (b[2] + b[3]))) + (((c[0] + c[1]) + (c[2] + c[3])) + ((d[0] + d[1]) + (d[2] + d[3])));
;     return rsqrtf(s * (1.0f / D) + RMS_EPS);
;     __device__ __forceinline__ void operator()(const Acc& acc, const pg8::Unit& u, int wr, int wc, int fr, int fq) const {
;     ...
;             for (int m = 0; m < 4; ++m) {
;                 const int row = u.pm * 256 + ai * 128 + wr * 64 + m * 16 + fr;
;                 const float rs = row_rs(part, row);
;                 if (u.pn < 4) {
; #pragma unroll
;                     for (int bj = 0; bj < 2; ++bj) { const int col = u.pn * 256 + bj * 128 + wc * 32 + 8 * fq;
;                         *(u32x4*)(bb + (size_t)row * D + col) = pack8(acc[ai][bj][m][0] * rs, acc[ai][bj][m][1] * rs); }
;                 } else {
;                     const int col = (u.pn - 4) * 128 + wc * 32 + 8 * fq;
;                     const f32x4 u0 = (acc[ai][0][m][0] * rs) * (acc[ai][1][m][0] * rs), u1 = (acc[ai][0][m][1] * rs) * (acc[ai][1][m][1] * rs);
;                     *(u32x4*)(ub + (size_t)row * D + col) = pack8(u0, u1);
.LBB0_199:
	v_or_b32_e32 v60, 16, v74
	v_ashrrev_i32_e32 v61, 31, v60
	v_lshlrev_b64 v[50:51], 6, v[60:61]
	v_lshl_add_u64 v[58:59], s[90:91], 0, v[50:51]
	s_mov_b64 s[30:31], -1
	s_and_b64 vcc, exec, s[2:3]
	v_lshlrev_b64 v[62:63], 11, v[60:61]
	s_nop 0
	s_nop 1
	s_nop 0
	s_waitcnt vmcnt(5)
	v_add_f32_e32 v178, v178, v179
	v_add_f32_e32 v180, v180, v181
	v_add_f32_e32 v182, v182, v183
	v_add_f32_e32 v184, v184, v185
	v_add_f32_e32 v186, v186, v187
	v_add_f32_e32 v188, v188, v189
	v_add_f32_e32 v195, v178, v180
	v_add_f32_e32 v196, v182, v184
	v_add_f32_e32 v197, v186, v188
	v_mov_b32_e32 v203, v195
	v_mov_b32_e32 v204, v196
	v_mov_b32_e32 v205, v197
	v_permlane16_swap_b32_e32 v195, v203
	v_permlane16_swap_b32_e32 v196, v204
	v_permlane16_swap_b32_e32 v197, v205
	v_add_f32_e32 v195, v195, v203
	v_add_f32_e32 v196, v196, v204
	v_add_f32_e32 v197, v197, v205
	v_mov_b32_e32 v203, v195
	v_mov_b32_e32 v204, v196
	v_mov_b32_e32 v205, v197
	v_permlane32_swap_b32_e32 v195, v203
	v_permlane32_swap_b32_e32 v196, v204
	v_permlane32_swap_b32_e32 v197, v205
	v_add_f32_e32 v195, v195, v203
	v_add_f32_e32 v196, v196, v204
	v_add_f32_e32 v197, v197, v205
	v_fmamk_f32 v195, v195, 0x3a800000, v169
	v_fmamk_f32 v196, v196, 0x3a800000, v169
	v_fmamk_f32 v197, v197, 0x3a800000, v169
	v_rsq_f32_e32 v195, v195
	v_rsq_f32_e32 v196, v196
	v_rsq_f32_e32 v197, v197
	v_mov_b32_e32 v58, v195
	s_cbranch_vccnz .LBB0_203
	v_pk_mul_f32 v[50:51], v[48:49], v[58:59] op_sel_hi:[1,0]
	v_pk_mul_f32 v[54:55], v[46:47], v[58:59] op_sel_hi:[1,0]
	v_pk_mul_f32 v[52:53], v[40:41], v[58:59] op_sel_hi:[1,0]
	v_pk_mul_f32 v[56:57], v[38:39], v[58:59] op_sel_hi:[1,0]
	v_pk_mul_f32 v[52:53], v[50:51], v[52:53]
	v_pk_mul_f32 v[50:51], v[54:55], v[56:57]
	v_pk_mul_f32 v[54:55], v[44:45], v[58:59] op_sel_hi:[1,0]
	v_pk_mul_f32 v[64:65], v[42:43], v[58:59] op_sel_hi:[1,0]
	v_pk_mul_f32 v[56:57], v[36:37], v[58:59] op_sel_hi:[1,0]
	v_pk_mul_f32 v[66:67], v[34:35], v[58:59] op_sel_hi:[1,0]
	v_pk_mul_f32 v[56:57], v[54:55], v[56:57]
	v_pk_mul_f32 v[54:55], v[64:65], v[66:67]
	v_lshl_add_u64 v[68:69], s[12:13], 0, v[62:63]
	v_cmp_lt_i32_e32 vcc, s54, v60
	v_cvt_pk_bf16_f32 v64, v50, v51
	v_cvt_pk_bf16_f32 v65, v52, v53
	v_cvt_pk_bf16_f32 v66, v54, v55
	v_cvt_pk_bf16_f32 v67, v56, v57
	v_lshl_add_u64 v[68:69], v[148:149], 1, v[68:69]
	s_and_b64 s[30:31], vcc, s[20:21]
	global_store_dwordx4 v[68:69], v[64:67], off
	s_and_saveexec_b64 s[4:5], s[30:31]
	s_cbranch_execz .LBB0_202
	v_add_u32_e32 v59, 0xffffc010, v74
	v_lshrrev_b32_e32 v59, 1, v59
	v_and_b32_e32 v59, 0x7ffffffe, v59
	v_add_u32_e32 v60, v59, v165
	v_mov_b32_e32 v61, v149
	v_lshlrev_b64 v[60:61], 12, v[60:61]
	v_lshl_add_u64 v[60:61], s[14:15], 0, v[60:61]
	v_lshl_add_u64 v[60:61], v[148:149], 2, v[60:61]
	global_store_dwordx4 v[60:61], v[50:53], off
	global_store_dwordx4 v[60:61], v[54:57], off offset:16

; __device__ __forceinline__ u32x4 pack8(const f32x4 a, const f32x4 b) { u32x4 w; w.x = cvt_pk_bf16(a[0], a[1]); w.y = cvt_pk_bf16(a[2], a[3]); w.z = cvt_pk_bf16(b[0], b[1]); w.w = cvt_pk_bf16(b[2], b[3]); return w; }
;     __device__ __forceinline__ void operator()(const Acc& acc, const pg8::Unit& u, int wr, int wc, int fr, int fq) const {
;     ...
;             for (int m = 0; m < 4; ++m) {
;                 const int row = u.pm * 256 + ai * 128 + wr * 64 + m * 16 + fr;
;                 const float rs = row_rs(part, row);
;                 if (u.pn < 4) {
; #pragma unroll
;                     for (int bj = 0; bj < 2; ++bj) { const int col = u.pn * 256 + bj * 128 + wc * 32 + 8 * fq;
;                         *(u32x4*)(bb + (size_t)row * D + col) = pack8(acc[ai][bj][m][0] * rs, acc[ai][bj][m][1] * rs); }
;                 } else {
;                     const int col = (u.pn - 4) * 128 + wc * 32 + 8 * fq;
;                     const f32x4 u0 = (acc[ai][0][m][0] * rs) * (acc[ai][1][m][0] * rs), u1 = (acc[ai][0][m][1] * rs) * (acc[ai][1][m][1] * rs);
;                     *(u32x4*)(ub + (size_t)row * D + col) = pack8(u0, u1);
.LBB0_205:
	v_or_b32_e32 v44, 32, v74
	v_ashrrev_i32_e32 v45, 31, v44
	v_lshlrev_b64 v[34:35], 6, v[44:45]
	v_lshl_add_u64 v[42:43], s[90:91], 0, v[34:35]
	s_mov_b64 s[30:31], -1
	s_and_b64 vcc, exec, s[2:3]
	v_lshlrev_b64 v[46:47], 11, v[44:45]
	s_nop 0
	s_nop 1
	s_nop 0
	v_mov_b32_e32 v42, v196
	s_cbranch_vccnz .LBB0_209
	v_pk_mul_f32 v[34:35], v[32:33], v[42:43] op_sel_hi:[1,0]
	v_pk_mul_f32 v[38:39], v[30:31], v[42:43] op_sel_hi:[1,0]
	v_pk_mul_f32 v[36:37], v[24:25], v[42:43] op_sel_hi:[1,0]
	v_pk_mul_f32 v[40:41], v[22:23], v[42:43] op_sel_hi:[1,0]
	v_pk_mul_f32 v[36:37], v[34:35], v[36:37]
	v_pk_mul_f32 v[34:35], v[38:39], v[40:41]
	v_pk_mul_f32 v[38:39], v[28:29], v[42:43] op_sel_hi:[1,0]
	v_pk_mul_f32 v[48:49], v[26:27], v[42:43] op_sel_hi:[1,0]
	v_pk_mul_f32 v[40:41], v[20:21], v[42:43] op_sel_hi:[1,0]
	v_pk_mul_f32 v[50:51], v[18:19], v[42:43] op_sel_hi:[1,0]
	v_pk_mul_f32 v[40:41], v[38:39], v[40:41]
	v_pk_mul_f32 v[38:39], v[48:49], v[50:51]
	v_lshl_add_u64 v[52:53], s[12:13], 0, v[46:47]
	v_cmp_lt_i32_e32 vcc, s54, v44
	v_cvt_pk_bf16_f32 v48, v34, v35
	v_cvt_pk_bf16_f32 v49, v36, v37
	v_cvt_pk_bf16_f32 v50, v38, v39
	v_cvt_pk_bf16_f32 v51, v40, v41
	v_lshl_add_u64 v[52:53], v[148:149], 1, v[52:53]
	s_and_b64 s[30:31], vcc, s[20:21]
	global_store_dwordx4 v[52:53], v[48:51], off
	s_and_saveexec_b64 s[4:5], s[30:31]
	s_cbranch_execz .LBB0_208
	v_add_u32_e32 v43, 0xffffc020, v74
	v_lshrrev_b32_e32 v43, 1, v43
	v_and_b32_e32 v43, 0x7ffffffe, v43
	v_add_u32_e32 v44, v43, v165
	v_mov_b32_e32 v45, v149
	v_lshlrev_b64 v[44:45], 12, v[44:45]
	v_lshl_add_u64 v[44:45], s[14:15], 0, v[44:45]
	v_lshl_add_u64 v[44:45], v[148:149], 2, v[44:45]
	global_store_dwordx4 v[44:45], v[34:37], off
	global_store_dwordx4 v[44:45], v[38:41], off offset:16

; __device__ __forceinline__ u32x4 pack8(const f32x4 a, const f32x4 b) { u32x4 w; w.x = cvt_pk_bf16(a[0], a[1]); w.y = cvt_pk_bf16(a[2], a[3]); w.z = cvt_pk_bf16(b[0], b[1]); w.w = cvt_pk_bf16(b[2], b[3]); return w; }
;     __device__ __forceinline__ void operator()(const Acc& acc, const pg8::Unit& u, int wr, int wc, int fr, int fq) const {
;     ...
;             for (int m = 0; m < 4; ++m) {
;                 const int row = u.pm * 256 + ai * 128 + wr * 64 + m * 16 + fr;
;                 const float rs = row_rs(part, row);
;                 if (u.pn < 4) {
; #pragma unroll
;                     for (int bj = 0; bj < 2; ++bj) { const int col = u.pn * 256 + bj * 128 + wc * 32 + 8 * fq;
;                         *(u32x4*)(bb + (size_t)row * D + col) = pack8(acc[ai][bj][m][0] * rs, acc[ai][bj][m][1] * rs); }
;                 } else {
;                     const int col = (u.pn - 4) * 128 + wc * 32 + 8 * fq;
;                     const f32x4 u0 = (acc[ai][0][m][0] * rs) * (acc[ai][1][m][0] * rs), u1 = (acc[ai][0][m][1] * rs) * (acc[ai][1][m][1] * rs);
;                     *(u32x4*)(ub + (size_t)row * D + col) = pack8(u0, u1);
.LBB0_211:
	v_or_b32_e32 v30, 48, v74
	v_ashrrev_i32_e32 v31, 31, v30
	v_lshlrev_b64 v[18:19], 6, v[30:31]
	v_lshl_add_u64 v[32:33], s[90:91], 0, v[18:19]
	s_nop 0
	s_mov_b64 s[30:31], -1
	s_and_b64 vcc, exec, s[2:3]
	v_lshlrev_b64 v[28:29], 11, v[30:31]
	s_nop 0
	s_nop 1
	s_nop 0
	v_mov_b32_e32 v26, v197
	s_cbranch_vccz .LBB0_214
	s_and_b64 vcc, exec, s[30:31]
	s_cbranch_vccnz .LBB0_219

; __device__ __forceinline__ u32x4 pack8(const f32x4 a, const f32x4 b) { u32x4 w; w.x = cvt_pk_bf16(a[0], a[1]); w.y = cvt_pk_bf16(a[2], a[3]); w.z = cvt_pk_bf16(b[0], b[1]); w.w = cvt_pk_bf16(b[2], b[3]); return w; }
;     __device__ __forceinline__ void operator()(const Acc& acc, const pg8::Unit& u, int wr, int wc, int fr, int fq) const {
;     ...
; #pragma unroll
;         for (int ai = 0; ai < 2; ++ai)
; #pragma unroll
;             for (int m = 0; m < 4; ++m) {
;                 const int row = u.pm * 256 + ai * 128 + wr * 64 + m * 16 + fr;
;                 const float* src = row < TP ? xp + (size_t)row * D : xs + (size_t)(row - TP) * D;
;                 float ss = 0.f;
; #pragma unroll
;                 for (int bj = 0; bj < 2; ++bj) { const int col = u.pn * 256 + bj * 128 + wc * 32 + 8 * fq;
;                     f32x4 r0, r1;
;                     if (MODE == 0) { r0 = *(const f32x4*)(src + col); r1 = *(const f32x4*)(src + col + 4); }
;                     else { const u32x4 w = *(const u32x4*)(xb + (size_t)row * D + col); r0 = (f32x4){bflo(w.x), bfhi(w.x), bflo(w.y), bfhi(w.y)}; r1 = (f32x4){bflo(w.z), bfhi(w.z), bflo(w.w), bfhi(w.w)}; }
;                     const f32x4 v0 = acc[ai][bj][m][0] + r0, v1 = acc[ai][bj][m][1] + r1;
;                     *(u32x4*)(xb + (size_t)row * D + col) = pack8(v0, v1);
;                     if (MODE != 2) {
;                         ss += ((v0[0] * v0[0] + v0[1] * v0[1]) + (v0[2] * v0[2] + v0[3] * v0[3])) + ((v1[0] * v1[0] + v1[1] * v1[1]) + (v1[2] * v1[2] + v1[3] * v1[3])); } }
;                 if (MODE != 2) { ss += __shfl_xor(ss, 16); ss += __shfl_xor(ss, 32);
;                     if (fq == 0) part[(size_t)row * 16 + u.pn * 4 + wc] = ss; }
.LBB0_456:
	s_lshl_b32 s9, s8, 8
	v_add_u32_e32 v150, s9, v1
	v_ashrrev_i32_e32 v151, 31, v150
	v_lshlrev_b64 v[152:153], 11, v[150:151]
	v_lshl_or_b32 v148, s6, 8, v161
	v_lshl_add_u64 v[152:153], s[88:89], 0, v[152:153]
	v_ashrrev_i32_e32 v149, 31, v148
	v_lshl_add_u64 v[176:177], v[148:149], 1, v[152:153]
	v_lshlrev_b32_e32 v234, 11, v150
	v_lshl_add_u32 v234, v148, 1, v234
	global_load_dwordx4 v[194:197], v234, s[88:89]
	global_load_dwordx4 v[198:201], v234, s[88:89] offset:256
	v_add_u32_e32 v235, 0x8000, v234
	global_load_dwordx4 v[202:205], v235, s[88:89]
	global_load_dwordx4 v[206:209], v235, s[88:89] offset:256
	v_add_u32_e32 v235, 0x10000, v234
	global_load_dwordx4 v[210:213], v235, s[88:89]
	global_load_dwordx4 v[214:217], v235, s[88:89] offset:256
	v_add_u32_e32 v235, 0x18000, v234
	global_load_dwordx4 v[218:221], v235, s[88:89]
	global_load_dwordx4 v[222:225], v235, s[88:89] offset:256
	v_and_b32_e32 v153, 64, v165
	v_xor_b32_e32 v152, 16, v165
	v_add_u32_e32 v153, 64, v153
	v_xor_b32_e32 v166, 32, v165
	v_cmp_lt_i32_e32 vcc, v152, v153
	s_waitcnt vmcnt(6)
	v_lshlrev_b32_e32 v178, 16, v196
	v_cndmask_b32_e32 v152, v165, v152, vcc
	v_cmp_lt_i32_e32 vcc, v166, v153
	v_lshlrev_b32_e32 v167, 2, v152
	v_lshlrev_b32_e32 v152, 16, v194
	v_cndmask_b32_e32 v153, v165, v166, vcc
	v_lshlrev_b32_e32 v166, 2, v153
	v_and_b32_e32 v153, 0xffff0000, v194
	v_lshlrev_b32_e32 v168, 16, v195
	v_and_b32_e32 v169, 0xffff0000, v195
	v_and_b32_e32 v179, 0xffff0000, v196
	v_lshlrev_b32_e32 v170, 16, v197
	v_and_b32_e32 v171, 0xffff0000, v197
	v_lshlrev_b32_e32 v180, 16, v198
	v_and_b32_e32 v181, 0xffff0000, v198
	v_lshlrev_b32_e32 v172, 16, v199
	v_and_b32_e32 v173, 0xffff0000, v199
	v_lshlrev_b32_e32 v182, 16, v200
	v_and_b32_e32 v183, 0xffff0000, v200
	v_lshlrev_b32_e32 v174, 16, v201
	v_and_b32_e32 v175, 0xffff0000, v201
	v_add_u32_e32 v235, 0x40000, v234
	global_load_dwordx4 v[194:197], v235, s[88:89]
	global_load_dwordx4 v[198:201], v235, s[88:89] offset:256
	v_pk_add_f32 v[184:185], v[128:129], v[168:169]
	v_pk_add_f32 v[152:153], v[126:127], v[152:153]
	v_pk_add_f32 v[186:187], v[124:125], v[170:171]
	v_pk_add_f32 v[170:171], v[122:123], v[178:179]
	v_pk_add_f32 v[172:173], v[112:113], v[172:173]
	v_pk_add_f32 v[178:179], v[110:111], v[180:181]
	v_pk_add_f32 v[174:175], v[108:109], v[174:175]
	v_pk_add_f32 v[180:181], v[106:107], v[182:183]
	v_cvt_pk_bf16_f32 v168, v152, v153
	v_cvt_pk_bf16_f32 v169, v184, v185
	v_mul_f32_e32 v153, v153, v153
	v_mul_f32_e32 v182, v185, v185
	v_mul_f32_e32 v183, v171, v171
	v_mul_f32_e32 v185, v187, v187
	v_mul_f32_e32 v188, v179, v179
	v_mul_f32_e32 v189, v173, v173
	v_mul_f32_e32 v190, v181, v181
	v_mul_f32_e32 v191, v175, v175
	v_fmac_f32_e32 v153, v152, v152
	v_fmac_f32_e32 v182, v184, v184
	v_fmac_f32_e32 v183, v170, v170
	v_fmac_f32_e32 v185, v186, v186
	v_fmac_f32_e32 v188, v178, v178
	v_fmac_f32_e32 v189, v172, v172
	v_fmac_f32_e32 v190, v180, v180
	v_fmac_f32_e32 v191, v174, v174
	v_add_f32_e32 v152, v153, v182
	v_add_f32_e32 v153, v183, v185
	v_add_f32_e32 v182, v188, v189
	v_add_f32_e32 v183, v190, v191
	v_add_f32_e32 v152, v152, v153
	v_add_f32_e32 v153, v182, v183
	v_add_f32_e32 v152, v152, v153
	ds_bpermute_b32 v153, v167, v152
	v_cvt_pk_bf16_f32 v170, v170, v171
	v_cvt_pk_bf16_f32 v171, v186, v187
	global_store_dwordx4 v[176:177], v[168:171], off
	s_waitcnt lgkmcnt(0)
	v_add_f32_e32 v152, v152, v153
	ds_bpermute_b32 v153, v166, v152
	v_cvt_pk_bf16_f32 v168, v178, v179
	v_cvt_pk_bf16_f32 v169, v172, v173
	v_cvt_pk_bf16_f32 v170, v180, v181
	v_cvt_pk_bf16_f32 v171, v174, v175
	global_store_dwordx4 v[176:177], v[168:171], off offset:256
	s_and_saveexec_b64 s[30:31], s[0:1]
	s_cbranch_execz .LBB0_458
	s_waitcnt lgkmcnt(0)
	v_add_f32_e32 v168, v152, v153
	s_lshl_b32 s34, s6, 2
	v_lshlrev_b64 v[152:153], 6, v[150:151]
	s_ashr_i32 s35, s34, 31
	v_lshl_add_u64 v[152:153], s[90:91], 0, v[152:153]
	v_lshl_add_u64 v[152:153], s[34:35], 2, v[152:153]
	s_lshl_b32 s34, s46, 2
	s_mov_b32 s35, s13
	v_lshl_add_u64 v[152:153], v[152:153], 0, s[34:35]
	global_store_dword v[152:153], v168, off
.LBB0_458:
	s_or_b64 exec, exec, s[30:31]
	v_add_u32_e32 v152, s9, v154
	s_waitcnt lgkmcnt(0)
	v_ashrrev_i32_e32 v153, 31, v152
	v_lshlrev_b64 v[168:169], 11, v[152:153]
	v_lshl_add_u64 v[168:169], s[88:89], 0, v[168:169]
	v_lshl_add_u64 v[176:177], v[148:149], 1, v[168:169]
	s_waitcnt vmcnt(8)
	v_lshlrev_b32_e32 v178, 16, v202
	v_and_b32_e32 v179, 0xffff0000, v202
	v_lshlrev_b32_e32 v168, 16, v203
	v_and_b32_e32 v169, 0xffff0000, v203
	v_lshlrev_b32_e32 v180, 16, v204
	v_and_b32_e32 v181, 0xffff0000, v204
	v_lshlrev_b32_e32 v170, 16, v205
	v_and_b32_e32 v171, 0xffff0000, v205
	v_lshlrev_b32_e32 v182, 16, v206
	v_and_b32_e32 v183, 0xffff0000, v206
	v_lshlrev_b32_e32 v172, 16, v207
	v_and_b32_e32 v173, 0xffff0000, v207
	v_lshlrev_b32_e32 v184, 16, v208
	v_and_b32_e32 v185, 0xffff0000, v208
	v_lshlrev_b32_e32 v174, 16, v209
	v_and_b32_e32 v175, 0xffff0000, v209
	v_add_u32_e32 v235, 0x48000, v234
	global_load_dwordx4 v[202:205], v235, s[88:89]
	global_load_dwordx4 v[206:209], v235, s[88:89] offset:256
	v_pk_add_f32 v[186:187], v[120:121], v[168:169]
	v_pk_add_f32 v[178:179], v[118:119], v[178:179]
	v_pk_add_f32 v[188:189], v[116:117], v[170:171]
	v_pk_add_f32 v[170:171], v[114:115], v[180:181]
	v_pk_add_f32 v[172:173], v[96:97], v[172:173]
	v_pk_add_f32 v[180:181], v[94:95], v[182:183]
	v_pk_add_f32 v[174:175], v[92:93], v[174:175]
	v_pk_add_f32 v[182:183], v[90:91], v[184:185]
	v_cvt_pk_bf16_f32 v168, v178, v179
	v_cvt_pk_bf16_f32 v169, v186, v187
	v_mul_f32_e32 v151, v179, v179
	v_mul_f32_e32 v179, v187, v187
	v_mul_f32_e32 v184, v171, v171
	v_mul_f32_e32 v185, v189, v189
	v_mul_f32_e32 v187, v181, v181
	v_mul_f32_e32 v190, v173, v173
	v_mul_f32_e32 v191, v183, v183
	v_mul_f32_e32 v192, v175, v175
	v_fmac_f32_e32 v151, v178, v178
	v_fmac_f32_e32 v179, v186, v186
	v_fmac_f32_e32 v184, v170, v170
	v_fmac_f32_e32 v185, v188, v188
	v_fmac_f32_e32 v187, v180, v180
	v_fmac_f32_e32 v190, v172, v172
	v_fmac_f32_e32 v191, v182, v182
	v_fmac_f32_e32 v192, v174, v174
	v_add_f32_e32 v151, v151, v179
	v_add_f32_e32 v178, v184, v185
	v_add_f32_e32 v179, v187, v190
	v_add_f32_e32 v184, v191, v192
	v_add_f32_e32 v151, v151, v178
	v_add_f32_e32 v178, v179, v184
	v_add_f32_e32 v151, v151, v178
	ds_bpermute_b32 v178, v167, v151
	v_cvt_pk_bf16_f32 v170, v170, v171
	v_cvt_pk_bf16_f32 v171, v188, v189
	global_store_dwordx4 v[176:177], v[168:171], off
	s_waitcnt lgkmcnt(0)
	v_add_f32_e32 v151, v151, v178
	ds_bpermute_b32 v168, v166, v151
	v_cvt_pk_bf16_f32 v170, v180, v181
	v_cvt_pk_bf16_f32 v171, v172, v173
	v_cvt_pk_bf16_f32 v172, v182, v183
	v_cvt_pk_bf16_f32 v173, v174, v175
	global_store_dwordx4 v[176:177], v[170:173], off offset:256
	s_and_saveexec_b64 s[30:31], s[0:1]
	s_cbranch_execz .LBB0_460
; __device__ __forceinline__ u32x4 pack8(const f32x4 a, const f32x4 b) { u32x4 w; w.x = cvt_pk_bf16(a[0], a[1]); w.y = cvt_pk_bf16(a[2], a[3]); w.z = cvt_pk_bf16(b[0], b[1]); w.w = cvt_pk_bf16(b[2], b[3]); return w; }
;     __device__ __forceinline__ void operator()(const Acc& acc, const pg8::Unit& u, int wr, int wc, int fr, int fq) const {
;     ...
; #pragma unroll
;         for (int ai = 0; ai < 2; ++ai)
; #pragma unroll
;             for (int m = 0; m < 4; ++m) {
;                 const int row = u.pm * 256 + ai * 128 + wr * 64 + m * 16 + fr;
;                 const float* src = row < TP ? xp + (size_t)row * D : xs + (size_t)(row - TP) * D;
;                 float ss = 0.f;
; #pragma unroll
;                 for (int bj = 0; bj < 2; ++bj) { const int col = u.pn * 256 + bj * 128 + wc * 32 + 8 * fq;
;                     f32x4 r0, r1;
;                     if (MODE == 0) { r0 = *(const f32x4*)(src + col); r1 = *(const f32x4*)(src + col + 4); }
;                     else { const u32x4 w = *(const u32x4*)(xb + (size_t)row * D + col); r0 = (f32x4){bflo(w.x), bfhi(w.x), bflo(w.y), bfhi(w.y)}; r1 = (f32x4){bflo(w.z), bfhi(w.z), bflo(w.w), bfhi(w.w)}; }
;                     const f32x4 v0 = acc[ai][bj][m][0] + r0, v1 = acc[ai][bj][m][1] + r1;
;                     *(u32x4*)(xb + (size_t)row * D + col) = pack8(v0, v1);
;                     if (MODE != 2) {
;                         ss += ((v0[0] * v0[0] + v0[1] * v0[1]) + (v0[2] * v0[2] + v0[3] * v0[3])) + ((v1[0] * v1[0] + v1[1] * v1[1]) + (v1[2] * v1[2] + v1[3] * v1[3])); } }
;                 if (MODE != 2) { ss += __shfl_xor(ss, 16); ss += __shfl_xor(ss, 32);
;                     if (fq == 0) part[(size_t)row * 16 + u.pn * 4 + wc] = ss; }
	s_lshl_b32 s34, s6, 2
	v_lshlrev_b64 v[152:153], 6, v[152:153]
	s_ashr_i32 s35, s34, 31
	v_lshl_add_u64 v[152:153], s[90:91], 0, v[152:153]
	v_lshl_add_u64 v[152:153], s[34:35], 2, v[152:153]
	s_lshl_b32 s34, s46, 2
	s_mov_b32 s35, s13
	s_waitcnt lgkmcnt(0)
	v_add_f32_e32 v151, v151, v168
	v_lshl_add_u64 v[152:153], v[152:153], 0, s[34:35]
	global_store_dword v[152:153], v151, off
.LBB0_460:
	s_or_b64 exec, exec, s[30:31]
	v_add_u32_e32 v152, s9, v155
	v_ashrrev_i32_e32 v153, 31, v152
	s_waitcnt lgkmcnt(0)
	v_lshlrev_b64 v[168:169], 11, v[152:153]
	v_lshl_add_u64 v[168:169], s[88:89], 0, v[168:169]
	v_lshl_add_u64 v[176:177], v[148:149], 1, v[168:169]
	s_waitcnt vmcnt(10)
	v_lshlrev_b32_e32 v178, 16, v210
	v_and_b32_e32 v179, 0xffff0000, v210
	v_lshlrev_b32_e32 v168, 16, v211
	v_and_b32_e32 v169, 0xffff0000, v211
	v_lshlrev_b32_e32 v180, 16, v212
	v_and_b32_e32 v181, 0xffff0000, v212
	v_lshlrev_b32_e32 v170, 16, v213
	v_and_b32_e32 v171, 0xffff0000, v213
	v_lshlrev_b32_e32 v182, 16, v214
	v_and_b32_e32 v183, 0xffff0000, v214
	v_lshlrev_b32_e32 v172, 16, v215
	v_and_b32_e32 v173, 0xffff0000, v215
	v_lshlrev_b32_e32 v184, 16, v216
	v_and_b32_e32 v185, 0xffff0000, v216
	v_lshlrev_b32_e32 v174, 16, v217
	v_and_b32_e32 v175, 0xffff0000, v217
	v_add_u32_e32 v235, 0x50000, v234
	global_load_dwordx4 v[210:213], v235, s[88:89]
	global_load_dwordx4 v[214:217], v235, s[88:89] offset:256
	v_pk_add_f32 v[186:187], v[104:105], v[168:169]
	v_pk_add_f32 v[178:179], v[102:103], v[178:179]
	v_pk_add_f32 v[188:189], v[100:101], v[170:171]
	v_pk_add_f32 v[170:171], v[98:99], v[180:181]
	v_pk_add_f32 v[172:173], v[80:81], v[172:173]
	v_pk_add_f32 v[180:181], v[78:79], v[182:183]
	v_pk_add_f32 v[174:175], v[76:77], v[174:175]
	v_pk_add_f32 v[182:183], v[74:75], v[184:185]
	v_cvt_pk_bf16_f32 v168, v178, v179
	v_cvt_pk_bf16_f32 v169, v186, v187
	v_mul_f32_e32 v151, v179, v179
	v_mul_f32_e32 v179, v187, v187
	v_mul_f32_e32 v184, v171, v171
	v_mul_f32_e32 v185, v189, v189
	v_mul_f32_e32 v187, v181, v181
	v_mul_f32_e32 v190, v173, v173
	v_mul_f32_e32 v191, v183, v183
	v_mul_f32_e32 v192, v175, v175
	v_fmac_f32_e32 v151, v178, v178
	v_fmac_f32_e32 v179, v186, v186
	v_fmac_f32_e32 v184, v170, v170
	v_fmac_f32_e32 v185, v188, v188
	v_fmac_f32_e32 v187, v180, v180
	v_fmac_f32_e32 v190, v172, v172
	v_fmac_f32_e32 v191, v182, v182
	v_fmac_f32_e32 v192, v174, v174
	v_add_f32_e32 v151, v151, v179
	v_add_f32_e32 v178, v184, v185
	v_add_f32_e32 v179, v187, v190
	v_add_f32_e32 v184, v191, v192
	v_add_f32_e32 v151, v151, v178
	v_add_f32_e32 v178, v179, v184
	v_add_f32_e32 v151, v151, v178
	ds_bpermute_b32 v178, v167, v151
	v_cvt_pk_bf16_f32 v170, v170, v171
	v_cvt_pk_bf16_f32 v171, v188, v189
	global_store_dwordx4 v[176:177], v[168:171], off
	s_waitcnt lgkmcnt(0)
	v_add_f32_e32 v151, v151, v178
	ds_bpermute_b32 v168, v166, v151
	v_cvt_pk_bf16_f32 v170, v180, v181
	v_cvt_pk_bf16_f32 v171, v172, v173
	v_cvt_pk_bf16_f32 v172, v182, v183
	v_cvt_pk_bf16_f32 v173, v174, v175
	global_store_dwordx4 v[176:177], v[170:173], off offset:256
	s_and_saveexec_b64 s[30:31], s[0:1]
	s_cbranch_execz .LBB0_462
	s_lshl_b32 s34, s6, 2
	v_lshlrev_b64 v[152:153], 6, v[152:153]
	s_ashr_i32 s35, s34, 31
	v_lshl_add_u64 v[152:153], s[90:91], 0, v[152:153]
	v_lshl_add_u64 v[152:153], s[34:35], 2, v[152:153]
	s_lshl_b32 s34, s46, 2
	s_mov_b32 s35, s13
	s_waitcnt lgkmcnt(0)
	v_add_f32_e32 v151, v151, v168
	v_lshl_add_u64 v[152:153], v[152:153], 0, s[34:35]
	global_store_dword v[152:153], v151, off
.LBB0_462:
	s_or_b64 exec, exec, s[30:31]
	v_add_u32_e32 v152, s9, v156
	v_ashrrev_i32_e32 v153, 31, v152
	s_waitcnt lgkmcnt(0)
	v_lshlrev_b64 v[168:169], 11, v[152:153]
	v_lshl_add_u64 v[168:169], s[88:89], 0, v[168:169]
	v_lshl_add_u64 v[176:177], v[148:149], 1, v[168:169]
	s_waitcnt vmcnt(12)
	v_lshlrev_b32_e32 v178, 16, v218
	v_and_b32_e32 v179, 0xffff0000, v218
	v_lshlrev_b32_e32 v168, 16, v219
	v_and_b32_e32 v169, 0xffff0000, v219
	v_lshlrev_b32_e32 v180, 16, v220
	v_and_b32_e32 v181, 0xffff0000, v220
	v_lshlrev_b32_e32 v170, 16, v221
	v_and_b32_e32 v171, 0xffff0000, v221
	v_lshlrev_b32_e32 v182, 16, v222
	v_and_b32_e32 v183, 0xffff0000, v222
	v_lshlrev_b32_e32 v172, 16, v223
	v_and_b32_e32 v173, 0xffff0000, v223
	v_lshlrev_b32_e32 v184, 16, v224
	v_and_b32_e32 v185, 0xffff0000, v224
	v_lshlrev_b32_e32 v174, 16, v225
	v_and_b32_e32 v175, 0xffff0000, v225
	v_add_u32_e32 v235, 0x58000, v234
	global_load_dwordx4 v[218:221], v235, s[88:89]
	global_load_dwordx4 v[222:225], v235, s[88:89] offset:256
	v_pk_add_f32 v[186:187], v[88:89], v[168:169]
	v_pk_add_f32 v[178:179], v[86:87], v[178:179]
	v_pk_add_f32 v[188:189], v[84:85], v[170:171]
	v_pk_add_f32 v[170:171], v[82:83], v[180:181]
	v_pk_add_f32 v[172:173], v[72:73], v[172:173]
	v_pk_add_f32 v[180:181], v[70:71], v[182:183]
	v_pk_add_f32 v[174:175], v[68:69], v[174:175]
	v_pk_add_f32 v[182:183], v[66:67], v[184:185]
	v_cvt_pk_bf16_f32 v168, v178, v179
	v_cvt_pk_bf16_f32 v169, v186, v187
	v_mul_f32_e32 v151, v179, v179
	v_mul_f32_e32 v179, v187, v187
	v_mul_f32_e32 v184, v171, v171
	v_mul_f32_e32 v185, v189, v189
	v_mul_f32_e32 v187, v181, v181
	v_mul_f32_e32 v190, v173, v173
	v_mul_f32_e32 v191, v183, v183
	v_mul_f32_e32 v192, v175, v175
	v_fmac_f32_e32 v151, v178, v178
	v_fmac_f32_e32 v179, v186, v186
	v_fmac_f32_e32 v184, v170, v170
	v_fmac_f32_e32 v185, v188, v188
	v_fmac_f32_e32 v187, v180, v180
	v_fmac_f32_e32 v190, v172, v172
	v_fmac_f32_e32 v191, v182, v182
	v_fmac_f32_e32 v192, v174, v174
	v_add_f32_e32 v151, v151, v179
	v_add_f32_e32 v178, v184, v185
	v_add_f32_e32 v179, v187, v190
	v_add_f32_e32 v184, v191, v192
	v_add_f32_e32 v151, v151, v178
	v_add_f32_e32 v178, v179, v184
	v_add_f32_e32 v151, v151, v178
	ds_bpermute_b32 v178, v167, v151
	v_cvt_pk_bf16_f32 v170, v170, v171
	v_cvt_pk_bf16_f32 v171, v188, v189
	global_store_dwordx4 v[176:177], v[168:171], off
	s_waitcnt lgkmcnt(0)
	v_add_f32_e32 v151, v151, v178
	ds_bpermute_b32 v168, v166, v151
	v_cvt_pk_bf16_f32 v170, v180, v181
	v_cvt_pk_bf16_f32 v171, v172, v173
	v_cvt_pk_bf16_f32 v172, v182, v183
	v_cvt_pk_bf16_f32 v173, v174, v175
	global_store_dwordx4 v[176:177], v[170:173], off offset:256
	s_and_saveexec_b64 s[30:31], s[0:1]
	s_cbranch_execz .LBB0_464
	s_lshl_b32 s34, s6, 2
	v_lshlrev_b64 v[152:153], 6, v[152:153]
	s_ashr_i32 s35, s34, 31
	v_lshl_add_u64 v[152:153], s[90:91], 0, v[152:153]
	v_lshl_add_u64 v[152:153], s[34:35], 2, v[152:153]
	s_lshl_b32 s34, s46, 2
	s_mov_b32 s35, s13
	s_waitcnt lgkmcnt(0)
	v_add_f32_e32 v151, v151, v168
	v_lshl_add_u64 v[152:153], v[152:153], 0, s[34:35]
	global_store_dword v[152:153], v151, off
; __device__ __forceinline__ u32x4 pack8(const f32x4 a, const f32x4 b) { u32x4 w; w.x = cvt_pk_bf16(a[0], a[1]); w.y = cvt_pk_bf16(a[2], a[3]); w.z = cvt_pk_bf16(b[0], b[1]); w.w = cvt_pk_bf16(b[2], b[3]); return w; }
;     __device__ __forceinline__ void operator()(const Acc& acc, const pg8::Unit& u, int wr, int wc, int fr, int fq) const {
;     ...
; #pragma unroll
;         for (int ai = 0; ai < 2; ++ai)
; #pragma unroll
;             for (int m = 0; m < 4; ++m) {
;                 const int row = u.pm * 256 + ai * 128 + wr * 64 + m * 16 + fr;
;                 const float* src = row < TP ? xp + (size_t)row * D : xs + (size_t)(row - TP) * D;
;                 float ss = 0.f;
; #pragma unroll
;                 for (int bj = 0; bj < 2; ++bj) { const int col = u.pn * 256 + bj * 128 + wc * 32 + 8 * fq;
;                     f32x4 r0, r1;
;                     if (MODE == 0) { r0 = *(const f32x4*)(src + col); r1 = *(const f32x4*)(src + col + 4); }
;                     else { const u32x4 w = *(const u32x4*)(xb + (size_t)row * D + col); r0 = (f32x4){bflo(w.x), bfhi(w.x), bflo(w.y), bfhi(w.y)}; r1 = (f32x4){bflo(w.z), bfhi(w.z), bflo(w.w), bfhi(w.w)}; }
;                     const f32x4 v0 = acc[ai][bj][m][0] + r0, v1 = acc[ai][bj][m][1] + r1;
;                     *(u32x4*)(xb + (size_t)row * D + col) = pack8(v0, v1);
;                     if (MODE != 2) {
;                         ss += ((v0[0] * v0[0] + v0[1] * v0[1]) + (v0[2] * v0[2] + v0[3] * v0[3])) + ((v1[0] * v1[0] + v1[1] * v1[1]) + (v1[2] * v1[2] + v1[3] * v1[3])); } }
;                 if (MODE != 2) { ss += __shfl_xor(ss, 16); ss += __shfl_xor(ss, 32);
;                     if (fq == 0) part[(size_t)row * 16 + u.pn * 4 + wc] = ss; }
.LBB0_464:
	s_or_b64 exec, exec, s[30:31]
	v_add_u32_e32 v152, 0x80, v150
	v_ashrrev_i32_e32 v153, 31, v152
	s_waitcnt lgkmcnt(0)
	v_lshlrev_b64 v[168:169], 11, v[152:153]
	v_lshl_add_u64 v[168:169], s[88:89], 0, v[168:169]
	v_lshl_add_u64 v[176:177], v[148:149], 1, v[168:169]
	s_waitcnt vmcnt(14)
	v_lshlrev_b32_e32 v178, 16, v194
	v_and_b32_e32 v179, 0xffff0000, v194
	v_lshlrev_b32_e32 v168, 16, v195
	v_and_b32_e32 v169, 0xffff0000, v195
	v_lshlrev_b32_e32 v180, 16, v196
	v_and_b32_e32 v181, 0xffff0000, v196
	v_lshlrev_b32_e32 v170, 16, v197
	v_and_b32_e32 v171, 0xffff0000, v197
	v_lshlrev_b32_e32 v182, 16, v198
	v_and_b32_e32 v183, 0xffff0000, v198
	v_lshlrev_b32_e32 v172, 16, v199
	v_and_b32_e32 v173, 0xffff0000, v199
	v_lshlrev_b32_e32 v184, 16, v200
	v_and_b32_e32 v185, 0xffff0000, v200
	v_lshlrev_b32_e32 v174, 16, v201
	v_and_b32_e32 v175, 0xffff0000, v201
	v_pk_add_f32 v[186:187], v[64:65], v[168:169]
	v_pk_add_f32 v[178:179], v[62:63], v[178:179]
	v_pk_add_f32 v[188:189], v[60:61], v[170:171]
	v_pk_add_f32 v[170:171], v[58:59], v[180:181]
	v_pk_add_f32 v[172:173], v[48:49], v[172:173]
	v_pk_add_f32 v[180:181], v[46:47], v[182:183]
	v_pk_add_f32 v[174:175], v[44:45], v[174:175]
	v_pk_add_f32 v[182:183], v[42:43], v[184:185]
	v_cvt_pk_bf16_f32 v168, v178, v179
	v_cvt_pk_bf16_f32 v169, v186, v187
	v_mul_f32_e32 v151, v179, v179
	v_mul_f32_e32 v179, v187, v187
	v_mul_f32_e32 v184, v171, v171
	v_mul_f32_e32 v185, v189, v189
	v_mul_f32_e32 v187, v181, v181
	v_mul_f32_e32 v190, v173, v173
	v_mul_f32_e32 v191, v183, v183
	v_mul_f32_e32 v192, v175, v175
	v_fmac_f32_e32 v151, v178, v178
	v_fmac_f32_e32 v179, v186, v186
	v_fmac_f32_e32 v184, v170, v170
	v_fmac_f32_e32 v185, v188, v188
	v_fmac_f32_e32 v187, v180, v180
	v_fmac_f32_e32 v190, v172, v172
	v_fmac_f32_e32 v191, v182, v182
	v_fmac_f32_e32 v192, v174, v174
	v_add_f32_e32 v151, v151, v179
	v_add_f32_e32 v178, v184, v185
	v_add_f32_e32 v179, v187, v190
	v_add_f32_e32 v184, v191, v192
	v_add_f32_e32 v151, v151, v178
	v_add_f32_e32 v178, v179, v184
	v_add_f32_e32 v151, v151, v178
	ds_bpermute_b32 v178, v167, v151
	v_cvt_pk_bf16_f32 v170, v170, v171
	v_cvt_pk_bf16_f32 v171, v188, v189
	global_store_dwordx4 v[176:177], v[168:171], off
	s_waitcnt lgkmcnt(0)
	v_add_f32_e32 v151, v151, v178
	ds_bpermute_b32 v168, v166, v151
	v_cvt_pk_bf16_f32 v170, v180, v181
	v_cvt_pk_bf16_f32 v171, v172, v173
	v_cvt_pk_bf16_f32 v172, v182, v183
	v_cvt_pk_bf16_f32 v173, v174, v175
	global_store_dwordx4 v[176:177], v[170:173], off offset:256
	s_and_saveexec_b64 s[30:31], s[0:1]
	s_cbranch_execz .LBB0_466
	s_lshl_b32 s34, s6, 2
	v_lshlrev_b64 v[152:153], 6, v[152:153]
	s_ashr_i32 s35, s34, 31
	v_lshl_add_u64 v[152:153], s[90:91], 0, v[152:153]
	v_lshl_add_u64 v[152:153], s[34:35], 2, v[152:153]
	s_lshl_b32 s34, s46, 2
	s_mov_b32 s35, s13
	s_waitcnt lgkmcnt(0)
	v_add_f32_e32 v151, v151, v168
	v_lshl_add_u64 v[152:153], v[152:153], 0, s[34:35]
	global_store_dword v[152:153], v151, off
.LBB0_466:
	s_or_b64 exec, exec, s[30:31]
	v_add_u32_e32 v152, 0x90, v150
	v_ashrrev_i32_e32 v153, 31, v152
	s_waitcnt lgkmcnt(0)
	v_lshlrev_b64 v[168:169], 11, v[152:153]
	v_lshl_add_u64 v[168:169], s[88:89], 0, v[168:169]
	v_lshl_add_u64 v[176:177], v[148:149], 1, v[168:169]
	s_waitcnt vmcnt(14)
	v_lshlrev_b32_e32 v178, 16, v202
	v_and_b32_e32 v179, 0xffff0000, v202
	v_lshlrev_b32_e32 v168, 16, v203
	v_and_b32_e32 v169, 0xffff0000, v203
	v_lshlrev_b32_e32 v180, 16, v204
	v_and_b32_e32 v181, 0xffff0000, v204
	v_lshlrev_b32_e32 v170, 16, v205
	v_and_b32_e32 v171, 0xffff0000, v205
	v_lshlrev_b32_e32 v182, 16, v206
	v_and_b32_e32 v183, 0xffff0000, v206
	v_lshlrev_b32_e32 v172, 16, v207
	v_and_b32_e32 v173, 0xffff0000, v207
	v_lshlrev_b32_e32 v184, 16, v208
	v_and_b32_e32 v185, 0xffff0000, v208
	v_lshlrev_b32_e32 v174, 16, v209
	v_and_b32_e32 v175, 0xffff0000, v209
	v_pk_add_f32 v[186:187], v[56:57], v[168:169]
	v_pk_add_f32 v[178:179], v[54:55], v[178:179]
	v_pk_add_f32 v[188:189], v[52:53], v[170:171]
	v_pk_add_f32 v[170:171], v[50:51], v[180:181]
	v_pk_add_f32 v[172:173], v[32:33], v[172:173]
	v_pk_add_f32 v[180:181], v[30:31], v[182:183]
	v_pk_add_f32 v[174:175], v[28:29], v[174:175]
	v_pk_add_f32 v[182:183], v[26:27], v[184:185]
	v_cvt_pk_bf16_f32 v168, v178, v179
	v_cvt_pk_bf16_f32 v169, v186, v187
	v_mul_f32_e32 v151, v179, v179
	v_mul_f32_e32 v179, v187, v187
	v_mul_f32_e32 v184, v171, v171
	v_mul_f32_e32 v185, v189, v189
	v_mul_f32_e32 v187, v181, v181
	v_mul_f32_e32 v190, v173, v173
	v_mul_f32_e32 v191, v183, v183
	v_mul_f32_e32 v192, v175, v175
	v_fmac_f32_e32 v151, v178, v178
	v_fmac_f32_e32 v179, v186, v186
	v_fmac_f32_e32 v184, v170, v170
	v_fmac_f32_e32 v185, v188, v188
	v_fmac_f32_e32 v187, v180, v180
	v_fmac_f32_e32 v190, v172, v172
	v_fmac_f32_e32 v191, v182, v182
	v_fmac_f32_e32 v192, v174, v174
	v_add_f32_e32 v151, v151, v179
	v_add_f32_e32 v178, v184, v185
	v_add_f32_e32 v179, v187, v190
	v_add_f32_e32 v184, v191, v192
	v_add_f32_e32 v151, v151, v178
	v_add_f32_e32 v178, v179, v184
	v_add_f32_e32 v151, v151, v178
	ds_bpermute_b32 v178, v167, v151
	v_cvt_pk_bf16_f32 v170, v170, v171
	v_cvt_pk_bf16_f32 v171, v188, v189
	global_store_dwordx4 v[176:177], v[168:171], off
	s_waitcnt lgkmcnt(0)
	v_add_f32_e32 v151, v151, v178
	ds_bpermute_b32 v168, v166, v151
	v_cvt_pk_bf16_f32 v170, v180, v181
	v_cvt_pk_bf16_f32 v171, v172, v173
	v_cvt_pk_bf16_f32 v172, v182, v183
	v_cvt_pk_bf16_f32 v173, v174, v175
	global_store_dwordx4 v[176:177], v[170:173], off offset:256
	s_and_saveexec_b64 s[30:31], s[0:1]
	s_cbranch_execz .LBB0_468
	s_lshl_b32 s34, s6, 2
	v_lshlrev_b64 v[152:153], 6, v[152:153]
	s_ashr_i32 s35, s34, 31
	v_lshl_add_u64 v[152:153], s[90:91], 0, v[152:153]
	v_lshl_add_u64 v[152:153], s[34:35], 2, v[152:153]
	s_lshl_b32 s34, s46, 2
	s_mov_b32 s35, s13
	s_waitcnt lgkmcnt(0)
	v_add_f32_e32 v151, v151, v168
	v_lshl_add_u64 v[152:153], v[152:153], 0, s[34:35]
	global_store_dword v[152:153], v151, off
; __device__ __forceinline__ u32x4 pack8(const f32x4 a, const f32x4 b) { u32x4 w; w.x = cvt_pk_bf16(a[0], a[1]); w.y = cvt_pk_bf16(a[2], a[3]); w.z = cvt_pk_bf16(b[0], b[1]); w.w = cvt_pk_bf16(b[2], b[3]); return w; }
;     __device__ __forceinline__ void operator()(const Acc& acc, const pg8::Unit& u, int wr, int wc, int fr, int fq) const {
;     ...
; #pragma unroll
;         for (int ai = 0; ai < 2; ++ai)
; #pragma unroll
;             for (int m = 0; m < 4; ++m) {
;                 const int row = u.pm * 256 + ai * 128 + wr * 64 + m * 16 + fr;
;                 const float* src = row < TP ? xp + (size_t)row * D : xs + (size_t)(row - TP) * D;
;                 float ss = 0.f;
; #pragma unroll
;                 for (int bj = 0; bj < 2; ++bj) { const int col = u.pn * 256 + bj * 128 + wc * 32 + 8 * fq;
;                     f32x4 r0, r1;
;                     if (MODE == 0) { r0 = *(const f32x4*)(src + col); r1 = *(const f32x4*)(src + col + 4); }
;                     else { const u32x4 w = *(const u32x4*)(xb + (size_t)row * D + col); r0 = (f32x4){bflo(w.x), bfhi(w.x), bflo(w.y), bfhi(w.y)}; r1 = (f32x4){bflo(w.z), bfhi(w.z), bflo(w.w), bfhi(w.w)}; }
;                     const f32x4 v0 = acc[ai][bj][m][0] + r0, v1 = acc[ai][bj][m][1] + r1;
;                     *(u32x4*)(xb + (size_t)row * D + col) = pack8(v0, v1);
;                     if (MODE != 2) {
;                         ss += ((v0[0] * v0[0] + v0[1] * v0[1]) + (v0[2] * v0[2] + v0[3] * v0[3])) + ((v1[0] * v1[0] + v1[1] * v1[1]) + (v1[2] * v1[2] + v1[3] * v1[3])); } }
;                 if (MODE != 2) { ss += __shfl_xor(ss, 16); ss += __shfl_xor(ss, 32);
;                     if (fq == 0) part[(size_t)row * 16 + u.pn * 4 + wc] = ss; }
.LBB0_468:
	s_or_b64 exec, exec, s[30:31]
	v_add_u32_e32 v152, 0xa0, v150
	v_ashrrev_i32_e32 v153, 31, v152
	s_waitcnt lgkmcnt(0)
	v_lshlrev_b64 v[168:169], 11, v[152:153]
	v_lshl_add_u64 v[168:169], s[88:89], 0, v[168:169]
	v_lshl_add_u64 v[176:177], v[148:149], 1, v[168:169]
	s_waitcnt vmcnt(14)
	v_lshlrev_b32_e32 v178, 16, v210
	v_and_b32_e32 v179, 0xffff0000, v210
	v_lshlrev_b32_e32 v168, 16, v211
	v_and_b32_e32 v169, 0xffff0000, v211
	v_lshlrev_b32_e32 v180, 16, v212
	v_and_b32_e32 v181, 0xffff0000, v212
	v_lshlrev_b32_e32 v170, 16, v213
	v_and_b32_e32 v171, 0xffff0000, v213
	v_lshlrev_b32_e32 v182, 16, v214
	v_and_b32_e32 v183, 0xffff0000, v214
	v_lshlrev_b32_e32 v172, 16, v215
	v_and_b32_e32 v173, 0xffff0000, v215
	v_lshlrev_b32_e32 v184, 16, v216
	v_and_b32_e32 v185, 0xffff0000, v216
	v_lshlrev_b32_e32 v174, 16, v217
	v_and_b32_e32 v175, 0xffff0000, v217
	v_pk_add_f32 v[186:187], v[40:41], v[168:169]
	v_pk_add_f32 v[178:179], v[38:39], v[178:179]
	v_pk_add_f32 v[188:189], v[36:37], v[170:171]
	v_pk_add_f32 v[170:171], v[34:35], v[180:181]
	v_pk_add_f32 v[172:173], v[16:17], v[172:173]
	v_pk_add_f32 v[180:181], v[14:15], v[182:183]
	v_pk_add_f32 v[174:175], v[12:13], v[174:175]
	v_pk_add_f32 v[182:183], v[10:11], v[184:185]
	v_cvt_pk_bf16_f32 v168, v178, v179
	v_cvt_pk_bf16_f32 v169, v186, v187
	v_mul_f32_e32 v151, v179, v179
	v_mul_f32_e32 v179, v187, v187
	v_mul_f32_e32 v184, v171, v171
	v_mul_f32_e32 v185, v189, v189
	v_mul_f32_e32 v187, v181, v181
	v_mul_f32_e32 v190, v173, v173
	v_mul_f32_e32 v191, v183, v183
	v_mul_f32_e32 v192, v175, v175
	v_fmac_f32_e32 v151, v178, v178
	v_fmac_f32_e32 v179, v186, v186
	v_fmac_f32_e32 v184, v170, v170
	v_fmac_f32_e32 v185, v188, v188
	v_fmac_f32_e32 v187, v180, v180
	v_fmac_f32_e32 v190, v172, v172
	v_fmac_f32_e32 v191, v182, v182
	v_fmac_f32_e32 v192, v174, v174
	v_add_f32_e32 v151, v151, v179
	v_add_f32_e32 v178, v184, v185
	v_add_f32_e32 v179, v187, v190
	v_add_f32_e32 v184, v191, v192
	v_add_f32_e32 v151, v151, v178
	v_add_f32_e32 v178, v179, v184
	v_add_f32_e32 v151, v151, v178
	ds_bpermute_b32 v178, v167, v151
	v_cvt_pk_bf16_f32 v170, v170, v171
	v_cvt_pk_bf16_f32 v171, v188, v189
	global_store_dwordx4 v[176:177], v[168:171], off
	s_waitcnt lgkmcnt(0)
	v_add_f32_e32 v151, v151, v178
	ds_bpermute_b32 v168, v166, v151
	v_cvt_pk_bf16_f32 v170, v180, v181
	v_cvt_pk_bf16_f32 v171, v172, v173
	v_cvt_pk_bf16_f32 v172, v182, v183
	v_cvt_pk_bf16_f32 v173, v174, v175
	global_store_dwordx4 v[176:177], v[170:173], off offset:256
	s_and_saveexec_b64 s[30:31], s[0:1]
	s_cbranch_execz .LBB0_470
	s_lshl_b32 s34, s6, 2
	v_lshlrev_b64 v[152:153], 6, v[152:153]
	s_ashr_i32 s35, s34, 31
	v_lshl_add_u64 v[152:153], s[90:91], 0, v[152:153]
	v_lshl_add_u64 v[152:153], s[34:35], 2, v[152:153]
	s_lshl_b32 s34, s46, 2
	s_mov_b32 s35, s13
	s_waitcnt lgkmcnt(0)
	v_add_f32_e32 v151, v151, v168
	v_lshl_add_u64 v[152:153], v[152:153], 0, s[34:35]
	global_store_dword v[152:153], v151, off
.LBB0_470:
	s_or_b64 exec, exec, s[30:31]
	v_add_u32_e32 v150, 0xb0, v150
	v_ashrrev_i32_e32 v151, 31, v150
	v_lshlrev_b64 v[152:153], 11, v[150:151]
	v_lshl_add_u64 v[152:153], s[88:89], 0, v[152:153]
	v_lshl_add_u64 v[152:153], v[148:149], 1, v[152:153]
	s_waitcnt lgkmcnt(0)
	s_waitcnt vmcnt(14)
	v_lshlrev_b32_e32 v148, 16, v218
	v_and_b32_e32 v149, 0xffff0000, v218
	v_lshlrev_b32_e32 v168, 16, v219
	v_and_b32_e32 v169, 0xffff0000, v219
	v_lshlrev_b32_e32 v176, 16, v220
	v_and_b32_e32 v177, 0xffff0000, v220
	v_lshlrev_b32_e32 v170, 16, v221
	v_and_b32_e32 v171, 0xffff0000, v221
	v_lshlrev_b32_e32 v178, 16, v222
	v_and_b32_e32 v179, 0xffff0000, v222
	v_lshlrev_b32_e32 v172, 16, v223
	v_and_b32_e32 v173, 0xffff0000, v223
	v_lshlrev_b32_e32 v180, 16, v224
	v_and_b32_e32 v181, 0xffff0000, v224
	v_lshlrev_b32_e32 v174, 16, v225
	v_and_b32_e32 v175, 0xffff0000, v225
	v_pk_add_f32 v[182:183], v[24:25], v[168:169]
	v_pk_add_f32 v[148:149], v[22:23], v[148:149]
	v_pk_add_f32 v[184:185], v[20:21], v[170:171]
	v_pk_add_f32 v[170:171], v[18:19], v[176:177]
	v_pk_add_f32 v[172:173], v[8:9], v[172:173]
	v_pk_add_f32 v[176:177], v[6:7], v[178:179]
	v_pk_add_f32 v[174:175], v[4:5], v[174:175]
	v_pk_add_f32 v[178:179], v[2:3], v[180:181]
	v_cvt_pk_bf16_f32 v168, v148, v149
	v_cvt_pk_bf16_f32 v169, v182, v183
	v_mul_f32_e32 v149, v149, v149
	v_mul_f32_e32 v180, v183, v183
	v_mul_f32_e32 v181, v171, v171
	v_mul_f32_e32 v183, v185, v185
	v_mul_f32_e32 v186, v177, v177
	v_mul_f32_e32 v187, v173, v173
	v_mul_f32_e32 v188, v179, v179
	v_mul_f32_e32 v189, v175, v175
	v_fmac_f32_e32 v149, v148, v148
	v_fmac_f32_e32 v180, v182, v182
	v_fmac_f32_e32 v181, v170, v170
	v_fmac_f32_e32 v183, v184, v184
	v_fmac_f32_e32 v186, v176, v176
	v_fmac_f32_e32 v187, v172, v172
	v_fmac_f32_e32 v188, v178, v178
	v_fmac_f32_e32 v189, v174, v174
	v_add_f32_e32 v148, v149, v180
	v_add_f32_e32 v149, v181, v183
	v_add_f32_e32 v180, v186, v187
	v_add_f32_e32 v181, v188, v189
	v_add_f32_e32 v148, v148, v149
	v_add_f32_e32 v149, v180, v181
	v_add_f32_e32 v148, v148, v149
	ds_bpermute_b32 v149, v167, v148
	v_cvt_pk_bf16_f32 v170, v170, v171
	v_cvt_pk_bf16_f32 v171, v184, v185
	global_store_dwordx4 v[152:153], v[168:171], off
	s_waitcnt lgkmcnt(0)
	v_add_f32_e32 v148, v148, v149
	ds_bpermute_b32 v149, v166, v148
	v_cvt_pk_bf16_f32 v168, v176, v177
	v_cvt_pk_bf16_f32 v169, v172, v173
	v_cvt_pk_bf16_f32 v170, v178, v179
	v_cvt_pk_bf16_f32 v171, v174, v175
	global_store_dwordx4 v[152:153], v[168:171], off offset:256
	s_and_saveexec_b64 s[30:31], s[0:1]
	s_cbranch_execz .LBB0_472
	s_waitcnt lgkmcnt(0)
	v_add_f32_e32 v152, v148, v149
	s_lshl_b32 s34, s6, 2
	v_lshlrev_b64 v[148:149], 6, v[150:151]
	s_ashr_i32 s35, s34, 31
	v_lshl_add_u64 v[148:149], s[90:91], 0, v[148:149]
	v_lshl_add_u64 v[148:149], s[34:35], 2, v[148:149]
	s_lshl_b32 s34, s46, 2
	s_mov_b32 s35, s13
	v_lshl_add_u64 v[148:149], v[148:149], 0, s[34:35]
	global_store_dword v[148:149], v152, off

; __device__ __forceinline__ u32x4 pack8(const f32x4 a, const f32x4 b) { u32x4 w; w.x = cvt_pk_bf16(a[0], a[1]); w.y = cvt_pk_bf16(a[2], a[3]); w.z = cvt_pk_bf16(b[0], b[1]); w.w = cvt_pk_bf16(b[2], b[3]); return w; }
;     __device__ __forceinline__ void operator()(const Acc& acc, const pg8::Unit& u, int wr, int wc, int fr, int fq) const {
;     ...
; #pragma unroll
;         for (int ai = 0; ai < 2; ++ai)
; #pragma unroll
;             for (int m = 0; m < 4; ++m) {
;                 const int row = u.pm * 256 + ai * 128 + wr * 64 + m * 16 + fr;
;                 const float* src = row < TP ? xp + (size_t)row * D : xs + (size_t)(row - TP) * D;
;                 float ss = 0.f;
; #pragma unroll
;                 for (int bj = 0; bj < 2; ++bj) { const int col = u.pn * 256 + bj * 128 + wc * 32 + 8 * fq;
;                     f32x4 r0, r1;
;                     if (MODE == 0) { r0 = *(const f32x4*)(src + col); r1 = *(const f32x4*)(src + col + 4); }
;                     else { const u32x4 w = *(const u32x4*)(xb + (size_t)row * D + col); r0 = (f32x4){bflo(w.x), bfhi(w.x), bflo(w.y), bfhi(w.y)}; r1 = (f32x4){bflo(w.z), bfhi(w.z), bflo(w.w), bfhi(w.w)}; }
;                     const f32x4 v0 = acc[ai][bj][m][0] + r0, v1 = acc[ai][bj][m][1] + r1;
;                     *(u32x4*)(xb + (size_t)row * D + col) = pack8(v0, v1);
;                     if (MODE != 2) {
;                         ss += ((v0[0] * v0[0] + v0[1] * v0[1]) + (v0[2] * v0[2] + v0[3] * v0[3])) + ((v1[0] * v1[0] + v1[1] * v1[1]) + (v1[2] * v1[2] + v1[3] * v1[3])); } }
;                 if (MODE != 2) { ss += __shfl_xor(ss, 16); ss += __shfl_xor(ss, 32);
;                     if (fq == 0) part[(size_t)row * 16 + u.pn * 4 + wc] = ss; }
.LBB0_705:
	s_lshl_b32 s7, s36, 8
	v_add_u32_e32 v150, s7, v1
	v_ashrrev_i32_e32 v151, 31, v150
	v_lshlrev_b64 v[152:153], 11, v[150:151]
	v_lshl_or_b32 v148, s35, 8, v162
	v_lshl_add_u64 v[152:153], s[88:89], 0, v[152:153]
	v_ashrrev_i32_e32 v149, 31, v148
	v_lshl_add_u64 v[178:179], v[148:149], 1, v[152:153]
	v_lshlrev_b32_e32 v236, 11, v150
	v_lshl_add_u32 v236, v148, 1, v236
	global_load_dwordx4 v[196:199], v236, s[88:89]
	global_load_dwordx4 v[200:203], v236, s[88:89] offset:256
	v_add_u32_e32 v237, 0x8000, v236
	global_load_dwordx4 v[204:207], v237, s[88:89]
	global_load_dwordx4 v[208:211], v237, s[88:89] offset:256
	v_add_u32_e32 v237, 0x10000, v236
	global_load_dwordx4 v[212:215], v237, s[88:89]
	global_load_dwordx4 v[216:219], v237, s[88:89] offset:256
	v_add_u32_e32 v237, 0x18000, v236
	global_load_dwordx4 v[220:223], v237, s[88:89]
	global_load_dwordx4 v[224:227], v237, s[88:89] offset:256
	v_and_b32_e32 v153, 64, v166
	v_xor_b32_e32 v152, 16, v166
	v_add_u32_e32 v153, 64, v153
	v_xor_b32_e32 v167, 32, v166
	v_cmp_lt_i32_e32 vcc, v152, v153
	s_waitcnt vmcnt(6)
	v_lshlrev_b32_e32 v180, 16, v198
	v_cndmask_b32_e32 v152, v166, v152, vcc
	v_cmp_lt_i32_e32 vcc, v167, v153
	v_lshlrev_b32_e32 v168, 2, v152
	v_lshlrev_b32_e32 v152, 16, v196
	v_cndmask_b32_e32 v153, v166, v167, vcc
	v_lshlrev_b32_e32 v167, 2, v153
	v_and_b32_e32 v153, 0xffff0000, v196
	v_lshlrev_b32_e32 v170, 16, v197
	v_and_b32_e32 v171, 0xffff0000, v197
	v_and_b32_e32 v181, 0xffff0000, v198
	v_lshlrev_b32_e32 v172, 16, v199
	v_and_b32_e32 v173, 0xffff0000, v199
	v_lshlrev_b32_e32 v182, 16, v200
	v_and_b32_e32 v183, 0xffff0000, v200
	v_lshlrev_b32_e32 v174, 16, v201
	v_and_b32_e32 v175, 0xffff0000, v201
	v_lshlrev_b32_e32 v184, 16, v202
	v_and_b32_e32 v185, 0xffff0000, v202
	v_lshlrev_b32_e32 v176, 16, v203
	v_and_b32_e32 v177, 0xffff0000, v203
	v_add_u32_e32 v237, 0x40000, v236
	global_load_dwordx4 v[196:199], v237, s[88:89]
	global_load_dwordx4 v[200:203], v237, s[88:89] offset:256
	v_pk_add_f32 v[186:187], v[128:129], v[170:171]
	v_pk_add_f32 v[152:153], v[126:127], v[152:153]
	v_pk_add_f32 v[188:189], v[124:125], v[172:173]
	v_pk_add_f32 v[172:173], v[122:123], v[180:181]
	v_pk_add_f32 v[174:175], v[112:113], v[174:175]
	v_pk_add_f32 v[180:181], v[110:111], v[182:183]
	v_pk_add_f32 v[176:177], v[108:109], v[176:177]
	v_pk_add_f32 v[182:183], v[106:107], v[184:185]
	v_cvt_pk_bf16_f32 v170, v152, v153
	v_cvt_pk_bf16_f32 v171, v186, v187
	v_mul_f32_e32 v153, v153, v153
	v_mul_f32_e32 v169, v187, v187
	v_mul_f32_e32 v184, v173, v173
	v_mul_f32_e32 v185, v189, v189
	v_mul_f32_e32 v187, v181, v181
	v_mul_f32_e32 v190, v175, v175
	v_mul_f32_e32 v191, v183, v183
	v_mul_f32_e32 v192, v177, v177
	v_fmac_f32_e32 v153, v152, v152
	v_fmac_f32_e32 v169, v186, v186
	v_fmac_f32_e32 v184, v172, v172
	v_fmac_f32_e32 v185, v188, v188
	v_fmac_f32_e32 v187, v180, v180
	v_fmac_f32_e32 v190, v174, v174
	v_fmac_f32_e32 v191, v182, v182
	v_fmac_f32_e32 v192, v176, v176
	v_add_f32_e32 v152, v153, v169
	v_add_f32_e32 v153, v184, v185
	v_add_f32_e32 v169, v187, v190
	v_add_f32_e32 v184, v191, v192
	v_add_f32_e32 v152, v152, v153
	v_add_f32_e32 v153, v169, v184
	v_add_f32_e32 v152, v152, v153
	ds_bpermute_b32 v153, v168, v152
	v_cvt_pk_bf16_f32 v172, v172, v173
	v_cvt_pk_bf16_f32 v173, v188, v189
	global_store_dwordx4 v[178:179], v[170:173], off
	s_waitcnt lgkmcnt(0)
	v_add_f32_e32 v152, v152, v153
	ds_bpermute_b32 v153, v167, v152
	v_cvt_pk_bf16_f32 v170, v180, v181
	v_cvt_pk_bf16_f32 v171, v174, v175
	v_cvt_pk_bf16_f32 v172, v182, v183
	v_cvt_pk_bf16_f32 v173, v176, v177
	global_store_dwordx4 v[178:179], v[170:173], off offset:256
	s_and_saveexec_b64 s[22:23], s[0:1]
	s_cbranch_execz .LBB0_707
	s_waitcnt lgkmcnt(0)
	v_add_f32_e32 v169, v152, v153
	s_lshl_b32 s24, s35, 2
	v_lshlrev_b64 v[152:153], 6, v[150:151]
	s_ashr_i32 s25, s24, 31
	v_lshl_add_u64 v[152:153], s[90:91], 0, v[152:153]
	v_lshl_add_u64 v[152:153], s[24:25], 2, v[152:153]
	s_lshl_b32 s24, s42, 2
	s_mov_b32 s25, s9
	v_lshl_add_u64 v[152:153], v[152:153], 0, s[24:25]
	global_store_dword v[152:153], v169, off
.LBB0_707:
	s_or_b64 exec, exec, s[22:23]
	v_add_u32_e32 v152, s7, v155
	s_waitcnt lgkmcnt(0)
	v_ashrrev_i32_e32 v153, 31, v152
	v_lshlrev_b64 v[170:171], 11, v[152:153]
	v_lshl_add_u64 v[170:171], s[88:89], 0, v[170:171]
	v_lshl_add_u64 v[178:179], v[148:149], 1, v[170:171]
	s_waitcnt vmcnt(8)
	v_lshlrev_b32_e32 v180, 16, v204
	v_and_b32_e32 v181, 0xffff0000, v204
	v_lshlrev_b32_e32 v170, 16, v205
	v_and_b32_e32 v171, 0xffff0000, v205
	v_lshlrev_b32_e32 v182, 16, v206
	v_and_b32_e32 v183, 0xffff0000, v206
	v_lshlrev_b32_e32 v172, 16, v207
	v_and_b32_e32 v173, 0xffff0000, v207
	v_lshlrev_b32_e32 v184, 16, v208
	v_and_b32_e32 v185, 0xffff0000, v208
	v_lshlrev_b32_e32 v174, 16, v209
	v_and_b32_e32 v175, 0xffff0000, v209
	v_lshlrev_b32_e32 v186, 16, v210
	v_and_b32_e32 v187, 0xffff0000, v210
	v_lshlrev_b32_e32 v176, 16, v211
	v_and_b32_e32 v177, 0xffff0000, v211
	v_add_u32_e32 v237, 0x48000, v236
	global_load_dwordx4 v[204:207], v237, s[88:89]
	global_load_dwordx4 v[208:211], v237, s[88:89] offset:256
	v_pk_add_f32 v[188:189], v[120:121], v[170:171]
	v_pk_add_f32 v[180:181], v[118:119], v[180:181]
	v_pk_add_f32 v[190:191], v[116:117], v[172:173]
	v_pk_add_f32 v[172:173], v[114:115], v[182:183]
	v_pk_add_f32 v[174:175], v[96:97], v[174:175]
	v_pk_add_f32 v[182:183], v[94:95], v[184:185]
	v_pk_add_f32 v[176:177], v[92:93], v[176:177]
	v_pk_add_f32 v[184:185], v[90:91], v[186:187]
	v_cvt_pk_bf16_f32 v170, v180, v181
	v_cvt_pk_bf16_f32 v171, v188, v189
	v_mul_f32_e32 v151, v181, v181
	v_mul_f32_e32 v169, v189, v189
	v_mul_f32_e32 v181, v173, v173
	v_mul_f32_e32 v186, v191, v191
	v_mul_f32_e32 v187, v183, v183
	v_mul_f32_e32 v189, v175, v175
	v_mul_f32_e32 v192, v185, v185
	v_mul_f32_e32 v193, v177, v177
	v_fmac_f32_e32 v151, v180, v180
	v_fmac_f32_e32 v169, v188, v188
	v_fmac_f32_e32 v181, v172, v172
	v_fmac_f32_e32 v186, v190, v190
	v_fmac_f32_e32 v187, v182, v182
	v_fmac_f32_e32 v189, v174, v174
	v_fmac_f32_e32 v192, v184, v184
	v_fmac_f32_e32 v193, v176, v176
	v_add_f32_e32 v151, v151, v169
	v_add_f32_e32 v169, v181, v186
	v_add_f32_e32 v180, v187, v189
	v_add_f32_e32 v181, v192, v193
	v_add_f32_e32 v151, v151, v169
	v_add_f32_e32 v169, v180, v181
	v_add_f32_e32 v151, v151, v169
	ds_bpermute_b32 v169, v168, v151
	v_cvt_pk_bf16_f32 v172, v172, v173
	v_cvt_pk_bf16_f32 v173, v190, v191
	global_store_dwordx4 v[178:179], v[170:173], off
	s_waitcnt lgkmcnt(0)
	v_add_f32_e32 v151, v151, v169
	ds_bpermute_b32 v169, v167, v151
	v_cvt_pk_bf16_f32 v170, v182, v183
	v_cvt_pk_bf16_f32 v171, v174, v175
	v_cvt_pk_bf16_f32 v172, v184, v185
	v_cvt_pk_bf16_f32 v173, v176, v177
	global_store_dwordx4 v[178:179], v[170:173], off offset:256
	s_and_saveexec_b64 s[22:23], s[0:1]
	s_cbranch_execz .LBB0_709
; __device__ __forceinline__ u32x4 pack8(const f32x4 a, const f32x4 b) { u32x4 w; w.x = cvt_pk_bf16(a[0], a[1]); w.y = cvt_pk_bf16(a[2], a[3]); w.z = cvt_pk_bf16(b[0], b[1]); w.w = cvt_pk_bf16(b[2], b[3]); return w; }
;     __device__ __forceinline__ void operator()(const Acc& acc, const pg8::Unit& u, int wr, int wc, int fr, int fq) const {
;     ...
; #pragma unroll
;         for (int ai = 0; ai < 2; ++ai)
; #pragma unroll
;             for (int m = 0; m < 4; ++m) {
;                 const int row = u.pm * 256 + ai * 128 + wr * 64 + m * 16 + fr;
;                 const float* src = row < TP ? xp + (size_t)row * D : xs + (size_t)(row - TP) * D;
;                 float ss = 0.f;
; #pragma unroll
;                 for (int bj = 0; bj < 2; ++bj) { const int col = u.pn * 256 + bj * 128 + wc * 32 + 8 * fq;
;                     f32x4 r0, r1;
;                     if (MODE == 0) { r0 = *(const f32x4*)(src + col); r1 = *(const f32x4*)(src + col + 4); }
;                     else { const u32x4 w = *(const u32x4*)(xb + (size_t)row * D + col); r0 = (f32x4){bflo(w.x), bfhi(w.x), bflo(w.y), bfhi(w.y)}; r1 = (f32x4){bflo(w.z), bfhi(w.z), bflo(w.w), bfhi(w.w)}; }
;                     const f32x4 v0 = acc[ai][bj][m][0] + r0, v1 = acc[ai][bj][m][1] + r1;
;                     *(u32x4*)(xb + (size_t)row * D + col) = pack8(v0, v1);
;                     if (MODE != 2) {
;                         ss += ((v0[0] * v0[0] + v0[1] * v0[1]) + (v0[2] * v0[2] + v0[3] * v0[3])) + ((v1[0] * v1[0] + v1[1] * v1[1]) + (v1[2] * v1[2] + v1[3] * v1[3])); } }
;                 if (MODE != 2) { ss += __shfl_xor(ss, 16); ss += __shfl_xor(ss, 32);
;                     if (fq == 0) part[(size_t)row * 16 + u.pn * 4 + wc] = ss; }
	s_lshl_b32 s24, s35, 2
	v_lshlrev_b64 v[152:153], 6, v[152:153]
	s_ashr_i32 s25, s24, 31
	v_lshl_add_u64 v[152:153], s[90:91], 0, v[152:153]
	v_lshl_add_u64 v[152:153], s[24:25], 2, v[152:153]
	s_lshl_b32 s24, s42, 2
	s_mov_b32 s25, s9
	s_waitcnt lgkmcnt(0)
	v_add_f32_e32 v151, v151, v169
	v_lshl_add_u64 v[152:153], v[152:153], 0, s[24:25]
	global_store_dword v[152:153], v151, off
.LBB0_709:
	s_or_b64 exec, exec, s[22:23]
	v_add_u32_e32 v152, s7, v156
	v_ashrrev_i32_e32 v153, 31, v152
	v_lshlrev_b64 v[170:171], 11, v[152:153]
	v_lshl_add_u64 v[170:171], s[88:89], 0, v[170:171]
	v_lshl_add_u64 v[178:179], v[148:149], 1, v[170:171]
	s_waitcnt vmcnt(10)
	v_lshlrev_b32_e32 v180, 16, v212
	v_and_b32_e32 v181, 0xffff0000, v212
	v_lshlrev_b32_e32 v170, 16, v213
	v_and_b32_e32 v171, 0xffff0000, v213
	v_lshlrev_b32_e32 v182, 16, v214
	v_and_b32_e32 v183, 0xffff0000, v214
	v_lshlrev_b32_e32 v172, 16, v215
	v_and_b32_e32 v173, 0xffff0000, v215
	v_lshlrev_b32_e32 v184, 16, v216
	v_and_b32_e32 v185, 0xffff0000, v216
	v_lshlrev_b32_e32 v174, 16, v217
	v_and_b32_e32 v175, 0xffff0000, v217
	v_lshlrev_b32_e32 v186, 16, v218
	v_and_b32_e32 v187, 0xffff0000, v218
	v_lshlrev_b32_e32 v176, 16, v219
	v_and_b32_e32 v177, 0xffff0000, v219
	v_add_u32_e32 v237, 0x50000, v236
	global_load_dwordx4 v[212:215], v237, s[88:89]
	global_load_dwordx4 v[216:219], v237, s[88:89] offset:256
	v_pk_add_f32 v[188:189], v[104:105], v[170:171]
	v_pk_add_f32 v[180:181], v[102:103], v[180:181]
	v_pk_add_f32 v[190:191], v[100:101], v[172:173]
	v_pk_add_f32 v[172:173], v[98:99], v[182:183]
	v_pk_add_f32 v[174:175], v[80:81], v[174:175]
	v_pk_add_f32 v[182:183], v[78:79], v[184:185]
	v_pk_add_f32 v[176:177], v[76:77], v[176:177]
	v_pk_add_f32 v[184:185], v[74:75], v[186:187]
	v_cvt_pk_bf16_f32 v170, v180, v181
	v_cvt_pk_bf16_f32 v171, v188, v189
	v_mul_f32_e32 v151, v181, v181
	s_waitcnt lgkmcnt(0)
	v_mul_f32_e32 v169, v189, v189
	v_mul_f32_e32 v181, v173, v173
	v_mul_f32_e32 v186, v191, v191
	v_mul_f32_e32 v187, v183, v183
	v_mul_f32_e32 v189, v175, v175
	v_mul_f32_e32 v192, v185, v185
	v_mul_f32_e32 v193, v177, v177
	v_fmac_f32_e32 v151, v180, v180
	v_fmac_f32_e32 v169, v188, v188
	v_fmac_f32_e32 v181, v172, v172
	v_fmac_f32_e32 v186, v190, v190
	v_fmac_f32_e32 v187, v182, v182
	v_fmac_f32_e32 v189, v174, v174
	v_fmac_f32_e32 v192, v184, v184
	v_fmac_f32_e32 v193, v176, v176
	v_add_f32_e32 v151, v151, v169
	v_add_f32_e32 v169, v181, v186
	v_add_f32_e32 v180, v187, v189
	v_add_f32_e32 v181, v192, v193
	v_add_f32_e32 v151, v151, v169
	v_add_f32_e32 v169, v180, v181
	v_add_f32_e32 v151, v151, v169
	ds_bpermute_b32 v169, v168, v151
	v_cvt_pk_bf16_f32 v172, v172, v173
	v_cvt_pk_bf16_f32 v173, v190, v191
	global_store_dwordx4 v[178:179], v[170:173], off
	s_waitcnt lgkmcnt(0)
	v_add_f32_e32 v151, v151, v169
	ds_bpermute_b32 v169, v167, v151
	v_cvt_pk_bf16_f32 v170, v182, v183
	v_cvt_pk_bf16_f32 v171, v174, v175
	v_cvt_pk_bf16_f32 v172, v184, v185
	v_cvt_pk_bf16_f32 v173, v176, v177
	global_store_dwordx4 v[178:179], v[170:173], off offset:256
	s_and_saveexec_b64 s[22:23], s[0:1]
	s_cbranch_execz .LBB0_711
	s_lshl_b32 s24, s35, 2
	v_lshlrev_b64 v[152:153], 6, v[152:153]
	s_ashr_i32 s25, s24, 31
	v_lshl_add_u64 v[152:153], s[90:91], 0, v[152:153]
	v_lshl_add_u64 v[152:153], s[24:25], 2, v[152:153]
	s_lshl_b32 s24, s42, 2
	s_mov_b32 s25, s9
	s_waitcnt lgkmcnt(0)
	v_add_f32_e32 v151, v151, v169
	v_lshl_add_u64 v[152:153], v[152:153], 0, s[24:25]
	global_store_dword v[152:153], v151, off
.LBB0_711:
	s_or_b64 exec, exec, s[22:23]
	v_add_u32_e32 v152, s7, v157
	v_ashrrev_i32_e32 v153, 31, v152
	v_lshlrev_b64 v[170:171], 11, v[152:153]
	v_lshl_add_u64 v[170:171], s[88:89], 0, v[170:171]
	v_lshl_add_u64 v[178:179], v[148:149], 1, v[170:171]
	s_waitcnt vmcnt(12)
	v_lshlrev_b32_e32 v180, 16, v220
	v_and_b32_e32 v181, 0xffff0000, v220
	v_lshlrev_b32_e32 v170, 16, v221
	v_and_b32_e32 v171, 0xffff0000, v221
	v_lshlrev_b32_e32 v182, 16, v222
	v_and_b32_e32 v183, 0xffff0000, v222
	v_lshlrev_b32_e32 v172, 16, v223
	v_and_b32_e32 v173, 0xffff0000, v223
	v_lshlrev_b32_e32 v184, 16, v224
	v_and_b32_e32 v185, 0xffff0000, v224
	v_lshlrev_b32_e32 v174, 16, v225
	v_and_b32_e32 v175, 0xffff0000, v225
	v_lshlrev_b32_e32 v186, 16, v226
	v_and_b32_e32 v187, 0xffff0000, v226
	v_lshlrev_b32_e32 v176, 16, v227
	v_and_b32_e32 v177, 0xffff0000, v227
	v_add_u32_e32 v237, 0x58000, v236
	global_load_dwordx4 v[220:223], v237, s[88:89]
	global_load_dwordx4 v[224:227], v237, s[88:89] offset:256
	v_pk_add_f32 v[188:189], v[88:89], v[170:171]
	v_pk_add_f32 v[180:181], v[86:87], v[180:181]
	v_pk_add_f32 v[190:191], v[84:85], v[172:173]
	v_pk_add_f32 v[172:173], v[82:83], v[182:183]
	v_pk_add_f32 v[174:175], v[72:73], v[174:175]
	v_pk_add_f32 v[182:183], v[70:71], v[184:185]
	v_pk_add_f32 v[176:177], v[68:69], v[176:177]
	v_pk_add_f32 v[184:185], v[66:67], v[186:187]
	v_cvt_pk_bf16_f32 v170, v180, v181
	v_cvt_pk_bf16_f32 v171, v188, v189
	v_mul_f32_e32 v151, v181, v181
	s_waitcnt lgkmcnt(0)
	v_mul_f32_e32 v169, v189, v189
	v_mul_f32_e32 v181, v173, v173
	v_mul_f32_e32 v186, v191, v191
	v_mul_f32_e32 v187, v183, v183
	v_mul_f32_e32 v189, v175, v175
	v_mul_f32_e32 v192, v185, v185
	v_mul_f32_e32 v193, v177, v177
	v_fmac_f32_e32 v151, v180, v180
	v_fmac_f32_e32 v169, v188, v188
	v_fmac_f32_e32 v181, v172, v172
	v_fmac_f32_e32 v186, v190, v190
	v_fmac_f32_e32 v187, v182, v182
	v_fmac_f32_e32 v189, v174, v174
	v_fmac_f32_e32 v192, v184, v184
	v_fmac_f32_e32 v193, v176, v176
	v_add_f32_e32 v151, v151, v169
	v_add_f32_e32 v169, v181, v186
	v_add_f32_e32 v180, v187, v189
	v_add_f32_e32 v181, v192, v193
	v_add_f32_e32 v151, v151, v169
	v_add_f32_e32 v169, v180, v181
	v_add_f32_e32 v151, v151, v169
	ds_bpermute_b32 v169, v168, v151
	v_cvt_pk_bf16_f32 v172, v172, v173
	v_cvt_pk_bf16_f32 v173, v190, v191
	global_store_dwordx4 v[178:179], v[170:173], off
	s_waitcnt lgkmcnt(0)
	v_add_f32_e32 v151, v151, v169
	ds_bpermute_b32 v169, v167, v151
	v_cvt_pk_bf16_f32 v170, v182, v183
	v_cvt_pk_bf16_f32 v171, v174, v175
	v_cvt_pk_bf16_f32 v172, v184, v185
	v_cvt_pk_bf16_f32 v173, v176, v177
	global_store_dwordx4 v[178:179], v[170:173], off offset:256
	s_and_saveexec_b64 s[22:23], s[0:1]
	s_cbranch_execz .LBB0_713
	s_lshl_b32 s24, s35, 2
	v_lshlrev_b64 v[152:153], 6, v[152:153]
	s_ashr_i32 s25, s24, 31
	v_lshl_add_u64 v[152:153], s[90:91], 0, v[152:153]
	v_lshl_add_u64 v[152:153], s[24:25], 2, v[152:153]
	s_lshl_b32 s24, s42, 2
	s_mov_b32 s25, s9
	s_waitcnt lgkmcnt(0)
	v_add_f32_e32 v151, v151, v169
	v_lshl_add_u64 v[152:153], v[152:153], 0, s[24:25]
	global_store_dword v[152:153], v151, off
; __device__ __forceinline__ u32x4 pack8(const f32x4 a, const f32x4 b) { u32x4 w; w.x = cvt_pk_bf16(a[0], a[1]); w.y = cvt_pk_bf16(a[2], a[3]); w.z = cvt_pk_bf16(b[0], b[1]); w.w = cvt_pk_bf16(b[2], b[3]); return w; }
;     __device__ __forceinline__ void operator()(const Acc& acc, const pg8::Unit& u, int wr, int wc, int fr, int fq) const {
;     ...
; #pragma unroll
;         for (int ai = 0; ai < 2; ++ai)
; #pragma unroll
;             for (int m = 0; m < 4; ++m) {
;                 const int row = u.pm * 256 + ai * 128 + wr * 64 + m * 16 + fr;
;                 const float* src = row < TP ? xp + (size_t)row * D : xs + (size_t)(row - TP) * D;
;                 float ss = 0.f;
; #pragma unroll
;                 for (int bj = 0; bj < 2; ++bj) { const int col = u.pn * 256 + bj * 128 + wc * 32 + 8 * fq;
;                     f32x4 r0, r1;
;                     if (MODE == 0) { r0 = *(const f32x4*)(src + col); r1 = *(const f32x4*)(src + col + 4); }
;                     else { const u32x4 w = *(const u32x4*)(xb + (size_t)row * D + col); r0 = (f32x4){bflo(w.x), bfhi(w.x), bflo(w.y), bfhi(w.y)}; r1 = (f32x4){bflo(w.z), bfhi(w.z), bflo(w.w), bfhi(w.w)}; }
;                     const f32x4 v0 = acc[ai][bj][m][0] + r0, v1 = acc[ai][bj][m][1] + r1;
;                     *(u32x4*)(xb + (size_t)row * D + col) = pack8(v0, v1);
;                     if (MODE != 2) {
;                         ss += ((v0[0] * v0[0] + v0[1] * v0[1]) + (v0[2] * v0[2] + v0[3] * v0[3])) + ((v1[0] * v1[0] + v1[1] * v1[1]) + (v1[2] * v1[2] + v1[3] * v1[3])); } }
;                 if (MODE != 2) { ss += __shfl_xor(ss, 16); ss += __shfl_xor(ss, 32);
;                     if (fq == 0) part[(size_t)row * 16 + u.pn * 4 + wc] = ss; }
.LBB0_713:
	s_or_b64 exec, exec, s[22:23]
	v_add_u32_e32 v152, 0x80, v150
	v_ashrrev_i32_e32 v153, 31, v152
	v_lshlrev_b64 v[170:171], 11, v[152:153]
	v_lshl_add_u64 v[170:171], s[88:89], 0, v[170:171]
	v_lshl_add_u64 v[178:179], v[148:149], 1, v[170:171]
	s_waitcnt vmcnt(14)
	v_lshlrev_b32_e32 v180, 16, v196
	v_and_b32_e32 v181, 0xffff0000, v196
	v_lshlrev_b32_e32 v170, 16, v197
	v_and_b32_e32 v171, 0xffff0000, v197
	v_lshlrev_b32_e32 v182, 16, v198
	v_and_b32_e32 v183, 0xffff0000, v198
	v_lshlrev_b32_e32 v172, 16, v199
	v_and_b32_e32 v173, 0xffff0000, v199
	v_lshlrev_b32_e32 v184, 16, v200
	v_and_b32_e32 v185, 0xffff0000, v200
	v_lshlrev_b32_e32 v174, 16, v201
	v_and_b32_e32 v175, 0xffff0000, v201
	v_lshlrev_b32_e32 v186, 16, v202
	v_and_b32_e32 v187, 0xffff0000, v202
	v_lshlrev_b32_e32 v176, 16, v203
	v_and_b32_e32 v177, 0xffff0000, v203
	v_pk_add_f32 v[188:189], v[64:65], v[170:171]
	v_pk_add_f32 v[180:181], v[62:63], v[180:181]
	v_pk_add_f32 v[190:191], v[60:61], v[172:173]
	v_pk_add_f32 v[172:173], v[58:59], v[182:183]
	v_pk_add_f32 v[174:175], v[48:49], v[174:175]
	v_pk_add_f32 v[182:183], v[46:47], v[184:185]
	v_pk_add_f32 v[176:177], v[44:45], v[176:177]
	v_pk_add_f32 v[184:185], v[42:43], v[186:187]
	v_cvt_pk_bf16_f32 v170, v180, v181
	v_cvt_pk_bf16_f32 v171, v188, v189
	v_mul_f32_e32 v151, v181, v181
	s_waitcnt lgkmcnt(0)
	v_mul_f32_e32 v169, v189, v189
	v_mul_f32_e32 v181, v173, v173
	v_mul_f32_e32 v186, v191, v191
	v_mul_f32_e32 v187, v183, v183
	v_mul_f32_e32 v189, v175, v175
	v_mul_f32_e32 v192, v185, v185
	v_mul_f32_e32 v193, v177, v177
	v_fmac_f32_e32 v151, v180, v180
	v_fmac_f32_e32 v169, v188, v188
	v_fmac_f32_e32 v181, v172, v172
	v_fmac_f32_e32 v186, v190, v190
	v_fmac_f32_e32 v187, v182, v182
	v_fmac_f32_e32 v189, v174, v174
	v_fmac_f32_e32 v192, v184, v184
	v_fmac_f32_e32 v193, v176, v176
	v_add_f32_e32 v151, v151, v169
	v_add_f32_e32 v169, v181, v186
	v_add_f32_e32 v180, v187, v189
	v_add_f32_e32 v181, v192, v193
	v_add_f32_e32 v151, v151, v169
	v_add_f32_e32 v169, v180, v181
	v_add_f32_e32 v151, v151, v169
	ds_bpermute_b32 v169, v168, v151
	v_cvt_pk_bf16_f32 v172, v172, v173
	v_cvt_pk_bf16_f32 v173, v190, v191
	global_store_dwordx4 v[178:179], v[170:173], off
	s_waitcnt lgkmcnt(0)
	v_add_f32_e32 v151, v151, v169
	ds_bpermute_b32 v169, v167, v151
	v_cvt_pk_bf16_f32 v170, v182, v183
	v_cvt_pk_bf16_f32 v171, v174, v175
	v_cvt_pk_bf16_f32 v172, v184, v185
	v_cvt_pk_bf16_f32 v173, v176, v177
	global_store_dwordx4 v[178:179], v[170:173], off offset:256
	s_and_saveexec_b64 s[22:23], s[0:1]
	s_cbranch_execz .LBB0_715
	s_lshl_b32 s24, s35, 2
	v_lshlrev_b64 v[152:153], 6, v[152:153]
	s_ashr_i32 s25, s24, 31
	v_lshl_add_u64 v[152:153], s[90:91], 0, v[152:153]
	v_lshl_add_u64 v[152:153], s[24:25], 2, v[152:153]
	s_lshl_b32 s24, s42, 2
	s_mov_b32 s25, s9
	s_waitcnt lgkmcnt(0)
	v_add_f32_e32 v151, v151, v169
	v_lshl_add_u64 v[152:153], v[152:153], 0, s[24:25]
	global_store_dword v[152:153], v151, off
.LBB0_715:
	s_or_b64 exec, exec, s[22:23]
	v_add_u32_e32 v152, 0x90, v150
	v_ashrrev_i32_e32 v153, 31, v152
	v_lshlrev_b64 v[170:171], 11, v[152:153]
	v_lshl_add_u64 v[170:171], s[88:89], 0, v[170:171]
	v_lshl_add_u64 v[178:179], v[148:149], 1, v[170:171]
	s_waitcnt vmcnt(14)
	v_lshlrev_b32_e32 v180, 16, v204
	v_and_b32_e32 v181, 0xffff0000, v204
	v_lshlrev_b32_e32 v170, 16, v205
	v_and_b32_e32 v171, 0xffff0000, v205
	v_lshlrev_b32_e32 v182, 16, v206
	v_and_b32_e32 v183, 0xffff0000, v206
	v_lshlrev_b32_e32 v172, 16, v207
	v_and_b32_e32 v173, 0xffff0000, v207
	v_lshlrev_b32_e32 v184, 16, v208
	v_and_b32_e32 v185, 0xffff0000, v208
	v_lshlrev_b32_e32 v174, 16, v209
	v_and_b32_e32 v175, 0xffff0000, v209
	v_lshlrev_b32_e32 v186, 16, v210
	v_and_b32_e32 v187, 0xffff0000, v210
	v_lshlrev_b32_e32 v176, 16, v211
	v_and_b32_e32 v177, 0xffff0000, v211
	v_pk_add_f32 v[188:189], v[56:57], v[170:171]
	v_pk_add_f32 v[180:181], v[54:55], v[180:181]
	v_pk_add_f32 v[190:191], v[52:53], v[172:173]
	v_pk_add_f32 v[172:173], v[50:51], v[182:183]
	v_pk_add_f32 v[174:175], v[32:33], v[174:175]
	v_pk_add_f32 v[182:183], v[30:31], v[184:185]
	v_pk_add_f32 v[176:177], v[28:29], v[176:177]
	v_pk_add_f32 v[184:185], v[26:27], v[186:187]
	v_cvt_pk_bf16_f32 v170, v180, v181
	v_cvt_pk_bf16_f32 v171, v188, v189
	v_mul_f32_e32 v151, v181, v181
	s_waitcnt lgkmcnt(0)
	v_mul_f32_e32 v169, v189, v189
	v_mul_f32_e32 v181, v173, v173
	v_mul_f32_e32 v186, v191, v191
	v_mul_f32_e32 v187, v183, v183
	v_mul_f32_e32 v189, v175, v175
	v_mul_f32_e32 v192, v185, v185
	v_mul_f32_e32 v193, v177, v177
	v_fmac_f32_e32 v151, v180, v180
	v_fmac_f32_e32 v169, v188, v188
	v_fmac_f32_e32 v181, v172, v172
	v_fmac_f32_e32 v186, v190, v190
	v_fmac_f32_e32 v187, v182, v182
	v_fmac_f32_e32 v189, v174, v174
	v_fmac_f32_e32 v192, v184, v184
	v_fmac_f32_e32 v193, v176, v176
	v_add_f32_e32 v151, v151, v169
	v_add_f32_e32 v169, v181, v186
	v_add_f32_e32 v180, v187, v189
	v_add_f32_e32 v181, v192, v193
	v_add_f32_e32 v151, v151, v169
	v_add_f32_e32 v169, v180, v181
	v_add_f32_e32 v151, v151, v169
	ds_bpermute_b32 v169, v168, v151
	v_cvt_pk_bf16_f32 v172, v172, v173
	v_cvt_pk_bf16_f32 v173, v190, v191
	global_store_dwordx4 v[178:179], v[170:173], off
	s_waitcnt lgkmcnt(0)
	v_add_f32_e32 v151, v151, v169
	ds_bpermute_b32 v169, v167, v151
	v_cvt_pk_bf16_f32 v170, v182, v183
	v_cvt_pk_bf16_f32 v171, v174, v175
	v_cvt_pk_bf16_f32 v172, v184, v185
	v_cvt_pk_bf16_f32 v173, v176, v177
	global_store_dwordx4 v[178:179], v[170:173], off offset:256
	s_and_saveexec_b64 s[22:23], s[0:1]
	s_cbranch_execz .LBB0_717
	s_lshl_b32 s24, s35, 2
	v_lshlrev_b64 v[152:153], 6, v[152:153]
	s_ashr_i32 s25, s24, 31
	v_lshl_add_u64 v[152:153], s[90:91], 0, v[152:153]
	v_lshl_add_u64 v[152:153], s[24:25], 2, v[152:153]
	s_lshl_b32 s24, s42, 2
	s_mov_b32 s25, s9
	s_waitcnt lgkmcnt(0)
	v_add_f32_e32 v151, v151, v169
	v_lshl_add_u64 v[152:153], v[152:153], 0, s[24:25]
	global_store_dword v[152:153], v151, off
; __device__ __forceinline__ u32x4 pack8(const f32x4 a, const f32x4 b) { u32x4 w; w.x = cvt_pk_bf16(a[0], a[1]); w.y = cvt_pk_bf16(a[2], a[3]); w.z = cvt_pk_bf16(b[0], b[1]); w.w = cvt_pk_bf16(b[2], b[3]); return w; }
;     __device__ __forceinline__ void operator()(const Acc& acc, const pg8::Unit& u, int wr, int wc, int fr, int fq) const {
;     ...
; #pragma unroll
;         for (int ai = 0; ai < 2; ++ai)
; #pragma unroll
;             for (int m = 0; m < 4; ++m) {
;                 const int row = u.pm * 256 + ai * 128 + wr * 64 + m * 16 + fr;
;                 const float* src = row < TP ? xp + (size_t)row * D : xs + (size_t)(row - TP) * D;
;                 float ss = 0.f;
; #pragma unroll
;                 for (int bj = 0; bj < 2; ++bj) { const int col = u.pn * 256 + bj * 128 + wc * 32 + 8 * fq;
;                     f32x4 r0, r1;
;                     if (MODE == 0) { r0 = *(const f32x4*)(src + col); r1 = *(const f32x4*)(src + col + 4); }
;                     else { const u32x4 w = *(const u32x4*)(xb + (size_t)row * D + col); r0 = (f32x4){bflo(w.x), bfhi(w.x), bflo(w.y), bfhi(w.y)}; r1 = (f32x4){bflo(w.z), bfhi(w.z), bflo(w.w), bfhi(w.w)}; }
;                     const f32x4 v0 = acc[ai][bj][m][0] + r0, v1 = acc[ai][bj][m][1] + r1;
;                     *(u32x4*)(xb + (size_t)row * D + col) = pack8(v0, v1);
;                     if (MODE != 2) {
;                         ss += ((v0[0] * v0[0] + v0[1] * v0[1]) + (v0[2] * v0[2] + v0[3] * v0[3])) + ((v1[0] * v1[0] + v1[1] * v1[1]) + (v1[2] * v1[2] + v1[3] * v1[3])); } }
;                 if (MODE != 2) { ss += __shfl_xor(ss, 16); ss += __shfl_xor(ss, 32);
;                     if (fq == 0) part[(size_t)row * 16 + u.pn * 4 + wc] = ss; }
.LBB0_717:
	s_or_b64 exec, exec, s[22:23]
	v_add_u32_e32 v152, 0xa0, v150
	v_ashrrev_i32_e32 v153, 31, v152
	v_lshlrev_b64 v[170:171], 11, v[152:153]
	v_lshl_add_u64 v[170:171], s[88:89], 0, v[170:171]
	v_lshl_add_u64 v[178:179], v[148:149], 1, v[170:171]
	s_waitcnt vmcnt(14)
	v_lshlrev_b32_e32 v180, 16, v212
	v_and_b32_e32 v181, 0xffff0000, v212
	v_lshlrev_b32_e32 v170, 16, v213
	v_and_b32_e32 v171, 0xffff0000, v213
	v_lshlrev_b32_e32 v182, 16, v214
	v_and_b32_e32 v183, 0xffff0000, v214
	v_lshlrev_b32_e32 v172, 16, v215
	v_and_b32_e32 v173, 0xffff0000, v215
	v_lshlrev_b32_e32 v184, 16, v216
	v_and_b32_e32 v185, 0xffff0000, v216
	v_lshlrev_b32_e32 v174, 16, v217
	v_and_b32_e32 v175, 0xffff0000, v217
	v_lshlrev_b32_e32 v186, 16, v218
	v_and_b32_e32 v187, 0xffff0000, v218
	v_lshlrev_b32_e32 v176, 16, v219
	v_and_b32_e32 v177, 0xffff0000, v219
	v_pk_add_f32 v[188:189], v[40:41], v[170:171]
	v_pk_add_f32 v[180:181], v[38:39], v[180:181]
	v_pk_add_f32 v[190:191], v[36:37], v[172:173]
	v_pk_add_f32 v[172:173], v[34:35], v[182:183]
	v_pk_add_f32 v[174:175], v[16:17], v[174:175]
	v_pk_add_f32 v[182:183], v[14:15], v[184:185]
	v_pk_add_f32 v[176:177], v[12:13], v[176:177]
	v_pk_add_f32 v[184:185], v[10:11], v[186:187]
	v_cvt_pk_bf16_f32 v170, v180, v181
	v_cvt_pk_bf16_f32 v171, v188, v189
	v_mul_f32_e32 v151, v181, v181
	s_waitcnt lgkmcnt(0)
	v_mul_f32_e32 v169, v189, v189
	v_mul_f32_e32 v181, v173, v173
	v_mul_f32_e32 v186, v191, v191
	v_mul_f32_e32 v187, v183, v183
	v_mul_f32_e32 v189, v175, v175
	v_mul_f32_e32 v192, v185, v185
	v_mul_f32_e32 v193, v177, v177
	v_fmac_f32_e32 v151, v180, v180
	v_fmac_f32_e32 v169, v188, v188
	v_fmac_f32_e32 v181, v172, v172
	v_fmac_f32_e32 v186, v190, v190
	v_fmac_f32_e32 v187, v182, v182
	v_fmac_f32_e32 v189, v174, v174
	v_fmac_f32_e32 v192, v184, v184
	v_fmac_f32_e32 v193, v176, v176
	v_add_f32_e32 v151, v151, v169
	v_add_f32_e32 v169, v181, v186
	v_add_f32_e32 v180, v187, v189
	v_add_f32_e32 v181, v192, v193
	v_add_f32_e32 v151, v151, v169
	v_add_f32_e32 v169, v180, v181
	v_add_f32_e32 v151, v151, v169
	ds_bpermute_b32 v169, v168, v151
	v_cvt_pk_bf16_f32 v172, v172, v173
	v_cvt_pk_bf16_f32 v173, v190, v191
	global_store_dwordx4 v[178:179], v[170:173], off
	s_waitcnt lgkmcnt(0)
	v_add_f32_e32 v151, v151, v169
	ds_bpermute_b32 v169, v167, v151
	v_cvt_pk_bf16_f32 v170, v182, v183
	v_cvt_pk_bf16_f32 v171, v174, v175
	v_cvt_pk_bf16_f32 v172, v184, v185
	v_cvt_pk_bf16_f32 v173, v176, v177
	global_store_dwordx4 v[178:179], v[170:173], off offset:256
	s_and_saveexec_b64 s[22:23], s[0:1]
	s_cbranch_execz .LBB0_719
	s_lshl_b32 s24, s35, 2
	v_lshlrev_b64 v[152:153], 6, v[152:153]
	s_ashr_i32 s25, s24, 31
	v_lshl_add_u64 v[152:153], s[90:91], 0, v[152:153]
	v_lshl_add_u64 v[152:153], s[24:25], 2, v[152:153]
	s_lshl_b32 s24, s42, 2
	s_mov_b32 s25, s9
	s_waitcnt lgkmcnt(0)
	v_add_f32_e32 v151, v151, v169
	v_lshl_add_u64 v[152:153], v[152:153], 0, s[24:25]
	global_store_dword v[152:153], v151, off
.LBB0_719:
	s_or_b64 exec, exec, s[22:23]
	v_add_u32_e32 v150, 0xb0, v150
	v_ashrrev_i32_e32 v151, 31, v150
	v_lshlrev_b64 v[152:153], 11, v[150:151]
	v_lshl_add_u64 v[152:153], s[88:89], 0, v[152:153]
	v_lshl_add_u64 v[152:153], v[148:149], 1, v[152:153]
	s_waitcnt vmcnt(14)
	v_lshlrev_b32_e32 v148, 16, v220
	v_and_b32_e32 v149, 0xffff0000, v220
	v_lshlrev_b32_e32 v170, 16, v221
	v_and_b32_e32 v171, 0xffff0000, v221
	v_lshlrev_b32_e32 v178, 16, v222
	v_and_b32_e32 v179, 0xffff0000, v222
	v_lshlrev_b32_e32 v172, 16, v223
	v_and_b32_e32 v173, 0xffff0000, v223
	v_lshlrev_b32_e32 v180, 16, v224
	v_and_b32_e32 v181, 0xffff0000, v224
	v_lshlrev_b32_e32 v174, 16, v225
	v_and_b32_e32 v175, 0xffff0000, v225
	v_lshlrev_b32_e32 v182, 16, v226
	v_and_b32_e32 v183, 0xffff0000, v226
	v_lshlrev_b32_e32 v176, 16, v227
	v_and_b32_e32 v177, 0xffff0000, v227
	v_pk_add_f32 v[184:185], v[24:25], v[170:171]
	v_pk_add_f32 v[148:149], v[22:23], v[148:149]
	v_pk_add_f32 v[186:187], v[20:21], v[172:173]
	v_pk_add_f32 v[172:173], v[18:19], v[178:179]
	v_pk_add_f32 v[174:175], v[8:9], v[174:175]
	v_pk_add_f32 v[178:179], v[6:7], v[180:181]
	v_pk_add_f32 v[176:177], v[4:5], v[176:177]
	v_pk_add_f32 v[180:181], v[2:3], v[182:183]
	v_cvt_pk_bf16_f32 v170, v148, v149
	v_cvt_pk_bf16_f32 v171, v184, v185
	v_mul_f32_e32 v149, v149, v149
	s_waitcnt lgkmcnt(0)
	v_mul_f32_e32 v169, v185, v185
	v_mul_f32_e32 v182, v173, v173
	v_mul_f32_e32 v183, v187, v187
	v_mul_f32_e32 v185, v179, v179
	v_mul_f32_e32 v188, v175, v175
	v_mul_f32_e32 v189, v181, v181
	v_mul_f32_e32 v190, v177, v177
	v_fmac_f32_e32 v149, v148, v148
	v_fmac_f32_e32 v169, v184, v184
	v_fmac_f32_e32 v182, v172, v172
	v_fmac_f32_e32 v183, v186, v186
	v_fmac_f32_e32 v185, v178, v178
	v_fmac_f32_e32 v188, v174, v174
	v_fmac_f32_e32 v189, v180, v180
	v_fmac_f32_e32 v190, v176, v176
	v_add_f32_e32 v148, v149, v169
	v_add_f32_e32 v149, v182, v183
	v_add_f32_e32 v169, v185, v188
	v_add_f32_e32 v182, v189, v190
	v_add_f32_e32 v148, v148, v149
	v_add_f32_e32 v149, v169, v182
	v_add_f32_e32 v148, v148, v149
	ds_bpermute_b32 v149, v168, v148
	v_cvt_pk_bf16_f32 v172, v172, v173
	v_cvt_pk_bf16_f32 v173, v186, v187
	global_store_dwordx4 v[152:153], v[170:173], off
	v_cvt_pk_bf16_f32 v168, v178, v179
	s_waitcnt lgkmcnt(0)
	v_add_f32_e32 v148, v148, v149
	ds_bpermute_b32 v149, v167, v148
	v_cvt_pk_bf16_f32 v169, v174, v175
	v_cvt_pk_bf16_f32 v170, v180, v181
	v_cvt_pk_bf16_f32 v171, v176, v177
	global_store_dwordx4 v[152:153], v[168:171], off offset:256
	s_and_saveexec_b64 s[22:23], s[0:1]
	s_cbranch_execz .LBB0_721
	s_waitcnt lgkmcnt(0)
	v_add_f32_e32 v152, v148, v149
	s_lshl_b32 s24, s35, 2
	v_lshlrev_b64 v[148:149], 6, v[150:151]
	s_ashr_i32 s25, s24, 31
	v_lshl_add_u64 v[148:149], s[90:91], 0, v[148:149]
	v_lshl_add_u64 v[148:149], s[24:25], 2, v[148:149]
	s_lshl_b32 s24, s42, 2
	s_mov_b32 s25, s9
	v_lshl_add_u64 v[148:149], v[148:149], 0, s[24:25]
	global_store_dword v[148:149], v152, off

; __device__ __forceinline__ u32x4 pack8(const f32x4 a, const f32x4 b) { u32x4 w; w.x = cvt_pk_bf16(a[0], a[1]); w.y = cvt_pk_bf16(a[2], a[3]); w.z = cvt_pk_bf16(b[0], b[1]); w.w = cvt_pk_bf16(b[2], b[3]); return w; }
;     __device__ __forceinline__ void operator()(const Acc& acc, const pg8::Unit& u, int wr, int wc, int fr, int fq) const {
;     ...
; #pragma unroll
;         for (int ai = 0; ai < 2; ++ai)
; #pragma unroll
;             for (int m = 0; m < 4; ++m) {
;                 const int row = u.pm * 256 + ai * 128 + wr * 64 + m * 16 + fr;
;                 const float* src = row < TP ? xp + (size_t)row * D : xs + (size_t)(row - TP) * D;
;                 float ss = 0.f;
; #pragma unroll
;                 for (int bj = 0; bj < 2; ++bj) { const int col = u.pn * 256 + bj * 128 + wc * 32 + 8 * fq;
;                     f32x4 r0, r1;
;                     if (MODE == 0) { r0 = *(const f32x4*)(src + col); r1 = *(const f32x4*)(src + col + 4); }
;                     else { const u32x4 w = *(const u32x4*)(xb + (size_t)row * D + col); r0 = (f32x4){bflo(w.x), bfhi(w.x), bflo(w.y), bfhi(w.y)}; r1 = (f32x4){bflo(w.z), bfhi(w.z), bflo(w.w), bfhi(w.w)}; }
;                     const f32x4 v0 = acc[ai][bj][m][0] + r0, v1 = acc[ai][bj][m][1] + r1;
;                     *(u32x4*)(xb + (size_t)row * D + col) = pack8(v0, v1);
;                     if (MODE != 2) {
;                         ss += ((v0[0] * v0[0] + v0[1] * v0[1]) + (v0[2] * v0[2] + v0[3] * v0[3])) + ((v1[0] * v1[0] + v1[1] * v1[1]) + (v1[2] * v1[2] + v1[3] * v1[3])); } }
;                 if (MODE != 2) { ss += __shfl_xor(ss, 16); ss += __shfl_xor(ss, 32);
;                     if (fq == 0) part[(size_t)row * 16 + u.pn * 4 + wc] = ss; }
.LBB0_1230:
	s_lshl_b32 s9, s8, 8
	v_add_u32_e32 v150, s9, v154
	v_ashrrev_i32_e32 v151, 31, v150
	v_lshlrev_b64 v[152:153], 11, v[150:151]
	v_lshl_or_b32 v148, s6, 8, v163
	v_lshl_add_u64 v[152:153], s[88:89], 0, v[152:153]
	v_ashrrev_i32_e32 v149, 31, v148
	v_lshl_add_u64 v[178:179], v[148:149], 1, v[152:153]
	v_lshlrev_b32_e32 v236, 11, v150
	v_lshl_add_u32 v236, v148, 1, v236
	global_load_dwordx4 v[196:199], v236, s[88:89]
	global_load_dwordx4 v[200:203], v236, s[88:89] offset:256
	v_add_u32_e32 v237, 0x8000, v236
	global_load_dwordx4 v[204:207], v237, s[88:89]
	global_load_dwordx4 v[208:211], v237, s[88:89] offset:256
	v_add_u32_e32 v237, 0x10000, v236
	global_load_dwordx4 v[212:215], v237, s[88:89]
	global_load_dwordx4 v[216:219], v237, s[88:89] offset:256
	v_add_u32_e32 v237, 0x18000, v236
	global_load_dwordx4 v[220:223], v237, s[88:89]
	global_load_dwordx4 v[224:227], v237, s[88:89] offset:256
	v_and_b32_e32 v153, 64, v167
	v_xor_b32_e32 v152, 16, v167
	v_add_u32_e32 v153, 64, v153
	v_xor_b32_e32 v168, 32, v167
	v_cmp_lt_i32_e32 vcc, v152, v153
	s_waitcnt vmcnt(6)
	v_lshlrev_b32_e32 v180, 16, v198
	v_cndmask_b32_e32 v152, v167, v152, vcc
	v_cmp_lt_i32_e32 vcc, v168, v153
	v_lshlrev_b32_e32 v169, 2, v152
	v_lshlrev_b32_e32 v152, 16, v196
	v_cndmask_b32_e32 v153, v167, v168, vcc
	v_lshlrev_b32_e32 v168, 2, v153
	v_and_b32_e32 v153, 0xffff0000, v196
	v_lshlrev_b32_e32 v170, 16, v197
	v_and_b32_e32 v171, 0xffff0000, v197
	v_and_b32_e32 v181, 0xffff0000, v198
	v_lshlrev_b32_e32 v172, 16, v199
	v_and_b32_e32 v173, 0xffff0000, v199
	v_lshlrev_b32_e32 v182, 16, v200
	v_and_b32_e32 v183, 0xffff0000, v200
	v_lshlrev_b32_e32 v174, 16, v201
	v_and_b32_e32 v175, 0xffff0000, v201
	v_lshlrev_b32_e32 v184, 16, v202
	v_and_b32_e32 v185, 0xffff0000, v202
	v_lshlrev_b32_e32 v176, 16, v203
	v_and_b32_e32 v177, 0xffff0000, v203
	v_add_u32_e32 v237, 0x40000, v236
	global_load_dwordx4 v[196:199], v237, s[88:89]
	global_load_dwordx4 v[200:203], v237, s[88:89] offset:256
	v_pk_add_f32 v[186:187], v[128:129], v[170:171]
	v_pk_add_f32 v[152:153], v[126:127], v[152:153]
	v_pk_add_f32 v[188:189], v[124:125], v[172:173]
	v_pk_add_f32 v[172:173], v[122:123], v[180:181]
	v_pk_add_f32 v[174:175], v[112:113], v[174:175]
	v_pk_add_f32 v[180:181], v[110:111], v[182:183]
	v_pk_add_f32 v[176:177], v[108:109], v[176:177]
	v_pk_add_f32 v[182:183], v[106:107], v[184:185]
	v_cvt_pk_bf16_f32 v170, v152, v153
	v_cvt_pk_bf16_f32 v171, v186, v187
	v_mul_f32_e32 v153, v153, v153
	v_mul_f32_e32 v184, v187, v187
	v_mul_f32_e32 v185, v173, v173
	v_mul_f32_e32 v187, v189, v189
	v_mul_f32_e32 v190, v181, v181
	v_mul_f32_e32 v191, v175, v175
	v_mul_f32_e32 v192, v183, v183
	v_mul_f32_e32 v193, v177, v177
	v_fmac_f32_e32 v153, v152, v152
	v_fmac_f32_e32 v184, v186, v186
	v_fmac_f32_e32 v185, v172, v172
	v_fmac_f32_e32 v187, v188, v188
	v_fmac_f32_e32 v190, v180, v180
	v_fmac_f32_e32 v191, v174, v174
	v_fmac_f32_e32 v192, v182, v182
	v_fmac_f32_e32 v193, v176, v176
	v_add_f32_e32 v152, v153, v184
	v_add_f32_e32 v153, v185, v187
	v_add_f32_e32 v184, v190, v191
	v_add_f32_e32 v185, v192, v193
	v_add_f32_e32 v152, v152, v153
	v_add_f32_e32 v153, v184, v185
	v_add_f32_e32 v152, v152, v153
	ds_bpermute_b32 v153, v169, v152
	v_cvt_pk_bf16_f32 v172, v172, v173
	v_cvt_pk_bf16_f32 v173, v188, v189
	global_store_dwordx4 v[178:179], v[170:173], off
	s_waitcnt lgkmcnt(0)
	v_add_f32_e32 v152, v152, v153
	ds_bpermute_b32 v153, v168, v152
	v_cvt_pk_bf16_f32 v170, v180, v181
	v_cvt_pk_bf16_f32 v171, v174, v175
	v_cvt_pk_bf16_f32 v172, v182, v183
	v_cvt_pk_bf16_f32 v173, v176, v177
	global_store_dwordx4 v[178:179], v[170:173], off offset:256
	s_and_saveexec_b64 s[30:31], s[0:1]
	s_cbranch_execz .LBB0_1232
	s_waitcnt lgkmcnt(0)
	v_add_f32_e32 v170, v152, v153
	s_lshl_b32 s34, s6, 2
	v_lshlrev_b64 v[152:153], 6, v[150:151]
	s_ashr_i32 s35, s34, 31
	v_lshl_add_u64 v[152:153], s[90:91], 0, v[152:153]
	v_lshl_add_u64 v[152:153], s[34:35], 2, v[152:153]
	s_lshl_b32 s34, s46, 2
	s_mov_b32 s35, s13
	v_lshl_add_u64 v[152:153], v[152:153], 0, s[34:35]
	global_store_dword v[152:153], v170, off
.LBB0_1232:
	s_or_b64 exec, exec, s[30:31]
	v_add_u32_e32 v152, s9, v156
	s_waitcnt lgkmcnt(0)
	v_ashrrev_i32_e32 v153, 31, v152
	v_lshlrev_b64 v[170:171], 11, v[152:153]
	v_lshl_add_u64 v[170:171], s[88:89], 0, v[170:171]
	v_lshl_add_u64 v[178:179], v[148:149], 1, v[170:171]
	s_waitcnt vmcnt(8)
	v_lshlrev_b32_e32 v180, 16, v204
	v_and_b32_e32 v181, 0xffff0000, v204
	v_lshlrev_b32_e32 v170, 16, v205
	v_and_b32_e32 v171, 0xffff0000, v205
	v_lshlrev_b32_e32 v182, 16, v206
	v_and_b32_e32 v183, 0xffff0000, v206
	v_lshlrev_b32_e32 v172, 16, v207
	v_and_b32_e32 v173, 0xffff0000, v207
	v_lshlrev_b32_e32 v184, 16, v208
	v_and_b32_e32 v185, 0xffff0000, v208
	v_lshlrev_b32_e32 v174, 16, v209
	v_and_b32_e32 v175, 0xffff0000, v209
	v_lshlrev_b32_e32 v186, 16, v210
	v_and_b32_e32 v187, 0xffff0000, v210
	v_lshlrev_b32_e32 v176, 16, v211
	v_and_b32_e32 v177, 0xffff0000, v211
	v_add_u32_e32 v237, 0x48000, v236
	global_load_dwordx4 v[204:207], v237, s[88:89]
	global_load_dwordx4 v[208:211], v237, s[88:89] offset:256
	v_pk_add_f32 v[188:189], v[120:121], v[170:171]
	v_pk_add_f32 v[180:181], v[118:119], v[180:181]
	v_pk_add_f32 v[190:191], v[116:117], v[172:173]
	v_pk_add_f32 v[172:173], v[114:115], v[182:183]
	v_pk_add_f32 v[174:175], v[96:97], v[174:175]
	v_pk_add_f32 v[182:183], v[94:95], v[184:185]
	v_pk_add_f32 v[176:177], v[92:93], v[176:177]
	v_pk_add_f32 v[184:185], v[90:91], v[186:187]
	v_cvt_pk_bf16_f32 v170, v180, v181
	v_cvt_pk_bf16_f32 v171, v188, v189
	v_mul_f32_e32 v151, v181, v181
	v_mul_f32_e32 v181, v189, v189
	v_mul_f32_e32 v186, v173, v173
	v_mul_f32_e32 v187, v191, v191
	v_mul_f32_e32 v189, v183, v183
	v_mul_f32_e32 v192, v175, v175
	v_mul_f32_e32 v193, v185, v185
	v_mul_f32_e32 v194, v177, v177
	v_fmac_f32_e32 v151, v180, v180
	v_fmac_f32_e32 v181, v188, v188
	v_fmac_f32_e32 v186, v172, v172
	v_fmac_f32_e32 v187, v190, v190
	v_fmac_f32_e32 v189, v182, v182
	v_fmac_f32_e32 v192, v174, v174
	v_fmac_f32_e32 v193, v184, v184
	v_fmac_f32_e32 v194, v176, v176
	v_add_f32_e32 v151, v151, v181
	v_add_f32_e32 v180, v186, v187
	v_add_f32_e32 v181, v189, v192
	v_add_f32_e32 v186, v193, v194
	v_add_f32_e32 v151, v151, v180
	v_add_f32_e32 v180, v181, v186
	v_add_f32_e32 v151, v151, v180
	ds_bpermute_b32 v180, v169, v151
	v_cvt_pk_bf16_f32 v172, v172, v173
	v_cvt_pk_bf16_f32 v173, v190, v191
	global_store_dwordx4 v[178:179], v[170:173], off
	s_waitcnt lgkmcnt(0)
	v_add_f32_e32 v151, v151, v180
	ds_bpermute_b32 v170, v168, v151
	v_cvt_pk_bf16_f32 v172, v182, v183
	v_cvt_pk_bf16_f32 v173, v174, v175
	v_cvt_pk_bf16_f32 v174, v184, v185
	v_cvt_pk_bf16_f32 v175, v176, v177
	global_store_dwordx4 v[178:179], v[172:175], off offset:256
	s_and_saveexec_b64 s[30:31], s[0:1]
	s_cbranch_execz .LBB0_1234
; __device__ __forceinline__ u32x4 pack8(const f32x4 a, const f32x4 b) { u32x4 w; w.x = cvt_pk_bf16(a[0], a[1]); w.y = cvt_pk_bf16(a[2], a[3]); w.z = cvt_pk_bf16(b[0], b[1]); w.w = cvt_pk_bf16(b[2], b[3]); return w; }
;     __device__ __forceinline__ void operator()(const Acc& acc, const pg8::Unit& u, int wr, int wc, int fr, int fq) const {
;     ...
; #pragma unroll
;         for (int ai = 0; ai < 2; ++ai)
; #pragma unroll
;             for (int m = 0; m < 4; ++m) {
;                 const int row = u.pm * 256 + ai * 128 + wr * 64 + m * 16 + fr;
;                 const float* src = row < TP ? xp + (size_t)row * D : xs + (size_t)(row - TP) * D;
;                 float ss = 0.f;
; #pragma unroll
;                 for (int bj = 0; bj < 2; ++bj) { const int col = u.pn * 256 + bj * 128 + wc * 32 + 8 * fq;
;                     f32x4 r0, r1;
;                     if (MODE == 0) { r0 = *(const f32x4*)(src + col); r1 = *(const f32x4*)(src + col + 4); }
;                     else { const u32x4 w = *(const u32x4*)(xb + (size_t)row * D + col); r0 = (f32x4){bflo(w.x), bfhi(w.x), bflo(w.y), bfhi(w.y)}; r1 = (f32x4){bflo(w.z), bfhi(w.z), bflo(w.w), bfhi(w.w)}; }
;                     const f32x4 v0 = acc[ai][bj][m][0] + r0, v1 = acc[ai][bj][m][1] + r1;
;                     *(u32x4*)(xb + (size_t)row * D + col) = pack8(v0, v1);
;                     if (MODE != 2) {
;                         ss += ((v0[0] * v0[0] + v0[1] * v0[1]) + (v0[2] * v0[2] + v0[3] * v0[3])) + ((v1[0] * v1[0] + v1[1] * v1[1]) + (v1[2] * v1[2] + v1[3] * v1[3])); } }
;                 if (MODE != 2) { ss += __shfl_xor(ss, 16); ss += __shfl_xor(ss, 32);
;                     if (fq == 0) part[(size_t)row * 16 + u.pn * 4 + wc] = ss; }
	s_lshl_b32 s34, s6, 2
	v_lshlrev_b64 v[152:153], 6, v[152:153]
	s_ashr_i32 s35, s34, 31
	v_lshl_add_u64 v[152:153], s[90:91], 0, v[152:153]
	v_lshl_add_u64 v[152:153], s[34:35], 2, v[152:153]
	s_lshl_b32 s34, s46, 2
	s_mov_b32 s35, s13
	s_waitcnt lgkmcnt(0)
	v_add_f32_e32 v151, v151, v170
	v_lshl_add_u64 v[152:153], v[152:153], 0, s[34:35]
	global_store_dword v[152:153], v151, off
.LBB0_1234:
	s_or_b64 exec, exec, s[30:31]
	v_add_u32_e32 v152, s9, v157
	v_ashrrev_i32_e32 v153, 31, v152
	s_waitcnt lgkmcnt(0)
	v_lshlrev_b64 v[170:171], 11, v[152:153]
	v_lshl_add_u64 v[170:171], s[88:89], 0, v[170:171]
	v_lshl_add_u64 v[178:179], v[148:149], 1, v[170:171]
	s_waitcnt vmcnt(10)
	v_lshlrev_b32_e32 v180, 16, v212
	v_and_b32_e32 v181, 0xffff0000, v212
	v_lshlrev_b32_e32 v170, 16, v213
	v_and_b32_e32 v171, 0xffff0000, v213
	v_lshlrev_b32_e32 v182, 16, v214
	v_and_b32_e32 v183, 0xffff0000, v214
	v_lshlrev_b32_e32 v172, 16, v215
	v_and_b32_e32 v173, 0xffff0000, v215
	v_lshlrev_b32_e32 v184, 16, v216
	v_and_b32_e32 v185, 0xffff0000, v216
	v_lshlrev_b32_e32 v174, 16, v217
	v_and_b32_e32 v175, 0xffff0000, v217
	v_lshlrev_b32_e32 v186, 16, v218
	v_and_b32_e32 v187, 0xffff0000, v218
	v_lshlrev_b32_e32 v176, 16, v219
	v_and_b32_e32 v177, 0xffff0000, v219
	v_add_u32_e32 v237, 0x50000, v236
	global_load_dwordx4 v[212:215], v237, s[88:89]
	global_load_dwordx4 v[216:219], v237, s[88:89] offset:256
	v_pk_add_f32 v[188:189], v[104:105], v[170:171]
	v_pk_add_f32 v[180:181], v[102:103], v[180:181]
	v_pk_add_f32 v[190:191], v[100:101], v[172:173]
	v_pk_add_f32 v[172:173], v[98:99], v[182:183]
	v_pk_add_f32 v[174:175], v[80:81], v[174:175]
	v_pk_add_f32 v[182:183], v[78:79], v[184:185]
	v_pk_add_f32 v[176:177], v[76:77], v[176:177]
	v_pk_add_f32 v[184:185], v[74:75], v[186:187]
	v_cvt_pk_bf16_f32 v170, v180, v181
	v_cvt_pk_bf16_f32 v171, v188, v189
	v_mul_f32_e32 v151, v181, v181
	v_mul_f32_e32 v181, v189, v189
	v_mul_f32_e32 v186, v173, v173
	v_mul_f32_e32 v187, v191, v191
	v_mul_f32_e32 v189, v183, v183
	v_mul_f32_e32 v192, v175, v175
	v_mul_f32_e32 v193, v185, v185
	v_mul_f32_e32 v194, v177, v177
	v_fmac_f32_e32 v151, v180, v180
	v_fmac_f32_e32 v181, v188, v188
	v_fmac_f32_e32 v186, v172, v172
	v_fmac_f32_e32 v187, v190, v190
	v_fmac_f32_e32 v189, v182, v182
	v_fmac_f32_e32 v192, v174, v174
	v_fmac_f32_e32 v193, v184, v184
	v_fmac_f32_e32 v194, v176, v176
	v_add_f32_e32 v151, v151, v181
	v_add_f32_e32 v180, v186, v187
	v_add_f32_e32 v181, v189, v192
	v_add_f32_e32 v186, v193, v194
	v_add_f32_e32 v151, v151, v180
	v_add_f32_e32 v180, v181, v186
	v_add_f32_e32 v151, v151, v180
	ds_bpermute_b32 v180, v169, v151
	v_cvt_pk_bf16_f32 v172, v172, v173
	v_cvt_pk_bf16_f32 v173, v190, v191
	global_store_dwordx4 v[178:179], v[170:173], off
	s_waitcnt lgkmcnt(0)
	v_add_f32_e32 v151, v151, v180
	ds_bpermute_b32 v170, v168, v151
	v_cvt_pk_bf16_f32 v172, v182, v183
	v_cvt_pk_bf16_f32 v173, v174, v175
	v_cvt_pk_bf16_f32 v174, v184, v185
	v_cvt_pk_bf16_f32 v175, v176, v177
	global_store_dwordx4 v[178:179], v[172:175], off offset:256
	s_and_saveexec_b64 s[30:31], s[0:1]
	s_cbranch_execz .LBB0_1236
	s_lshl_b32 s34, s6, 2
	v_lshlrev_b64 v[152:153], 6, v[152:153]
	s_ashr_i32 s35, s34, 31
	v_lshl_add_u64 v[152:153], s[90:91], 0, v[152:153]
	v_lshl_add_u64 v[152:153], s[34:35], 2, v[152:153]
	s_lshl_b32 s34, s46, 2
	s_mov_b32 s35, s13
	s_waitcnt lgkmcnt(0)
	v_add_f32_e32 v151, v151, v170
	v_lshl_add_u64 v[152:153], v[152:153], 0, s[34:35]
	global_store_dword v[152:153], v151, off
.LBB0_1236:
	s_or_b64 exec, exec, s[30:31]
	v_add_u32_e32 v152, s9, v158
	v_ashrrev_i32_e32 v153, 31, v152
	s_waitcnt lgkmcnt(0)
	v_lshlrev_b64 v[170:171], 11, v[152:153]
	v_lshl_add_u64 v[170:171], s[88:89], 0, v[170:171]
	v_lshl_add_u64 v[178:179], v[148:149], 1, v[170:171]
	s_waitcnt vmcnt(12)
	v_lshlrev_b32_e32 v180, 16, v220
	v_and_b32_e32 v181, 0xffff0000, v220
	v_lshlrev_b32_e32 v170, 16, v221
	v_and_b32_e32 v171, 0xffff0000, v221
	v_lshlrev_b32_e32 v182, 16, v222
	v_and_b32_e32 v183, 0xffff0000, v222
	v_lshlrev_b32_e32 v172, 16, v223
	v_and_b32_e32 v173, 0xffff0000, v223
	v_lshlrev_b32_e32 v184, 16, v224
	v_and_b32_e32 v185, 0xffff0000, v224
	v_lshlrev_b32_e32 v174, 16, v225
	v_and_b32_e32 v175, 0xffff0000, v225
	v_lshlrev_b32_e32 v186, 16, v226
	v_and_b32_e32 v187, 0xffff0000, v226
	v_lshlrev_b32_e32 v176, 16, v227
	v_and_b32_e32 v177, 0xffff0000, v227
	v_add_u32_e32 v237, 0x58000, v236
	global_load_dwordx4 v[220:223], v237, s[88:89]
	global_load_dwordx4 v[224:227], v237, s[88:89] offset:256
	v_pk_add_f32 v[188:189], v[88:89], v[170:171]
	v_pk_add_f32 v[180:181], v[86:87], v[180:181]
	v_pk_add_f32 v[190:191], v[84:85], v[172:173]
	v_pk_add_f32 v[172:173], v[82:83], v[182:183]
	v_pk_add_f32 v[174:175], v[72:73], v[174:175]
	v_pk_add_f32 v[182:183], v[70:71], v[184:185]
	v_pk_add_f32 v[176:177], v[68:69], v[176:177]
	v_pk_add_f32 v[184:185], v[66:67], v[186:187]
	v_cvt_pk_bf16_f32 v170, v180, v181
	v_cvt_pk_bf16_f32 v171, v188, v189
	v_mul_f32_e32 v151, v181, v181
	v_mul_f32_e32 v181, v189, v189
	v_mul_f32_e32 v186, v173, v173
	v_mul_f32_e32 v187, v191, v191
	v_mul_f32_e32 v189, v183, v183
	v_mul_f32_e32 v192, v175, v175
	v_mul_f32_e32 v193, v185, v185
	v_mul_f32_e32 v194, v177, v177
	v_fmac_f32_e32 v151, v180, v180
	v_fmac_f32_e32 v181, v188, v188
	v_fmac_f32_e32 v186, v172, v172
	v_fmac_f32_e32 v187, v190, v190
	v_fmac_f32_e32 v189, v182, v182
	v_fmac_f32_e32 v192, v174, v174
	v_fmac_f32_e32 v193, v184, v184
	v_fmac_f32_e32 v194, v176, v176
	v_add_f32_e32 v151, v151, v181
	v_add_f32_e32 v180, v186, v187
	v_add_f32_e32 v181, v189, v192
	v_add_f32_e32 v186, v193, v194
	v_add_f32_e32 v151, v151, v180
	v_add_f32_e32 v180, v181, v186
	v_add_f32_e32 v151, v151, v180
	ds_bpermute_b32 v180, v169, v151
	v_cvt_pk_bf16_f32 v172, v172, v173
	v_cvt_pk_bf16_f32 v173, v190, v191
	global_store_dwordx4 v[178:179], v[170:173], off
	s_waitcnt lgkmcnt(0)
	v_add_f32_e32 v151, v151, v180
	ds_bpermute_b32 v170, v168, v151
	v_cvt_pk_bf16_f32 v172, v182, v183
	v_cvt_pk_bf16_f32 v173, v174, v175
	v_cvt_pk_bf16_f32 v174, v184, v185
	v_cvt_pk_bf16_f32 v175, v176, v177
	global_store_dwordx4 v[178:179], v[172:175], off offset:256
	s_and_saveexec_b64 s[30:31], s[0:1]
	s_cbranch_execz .LBB0_1238
	s_lshl_b32 s34, s6, 2
	v_lshlrev_b64 v[152:153], 6, v[152:153]
	s_ashr_i32 s35, s34, 31
	v_lshl_add_u64 v[152:153], s[90:91], 0, v[152:153]
	v_lshl_add_u64 v[152:153], s[34:35], 2, v[152:153]
	s_lshl_b32 s34, s46, 2
	s_mov_b32 s35, s13
	s_waitcnt lgkmcnt(0)
	v_add_f32_e32 v151, v151, v170
	v_lshl_add_u64 v[152:153], v[152:153], 0, s[34:35]
	global_store_dword v[152:153], v151, off
; __device__ __forceinline__ u32x4 pack8(const f32x4 a, const f32x4 b) { u32x4 w; w.x = cvt_pk_bf16(a[0], a[1]); w.y = cvt_pk_bf16(a[2], a[3]); w.z = cvt_pk_bf16(b[0], b[1]); w.w = cvt_pk_bf16(b[2], b[3]); return w; }
;     __device__ __forceinline__ void operator()(const Acc& acc, const pg8::Unit& u, int wr, int wc, int fr, int fq) const {
;     ...
; #pragma unroll
;         for (int ai = 0; ai < 2; ++ai)
; #pragma unroll
;             for (int m = 0; m < 4; ++m) {
;                 const int row = u.pm * 256 + ai * 128 + wr * 64 + m * 16 + fr;
;                 const float* src = row < TP ? xp + (size_t)row * D : xs + (size_t)(row - TP) * D;
;                 float ss = 0.f;
; #pragma unroll
;                 for (int bj = 0; bj < 2; ++bj) { const int col = u.pn * 256 + bj * 128 + wc * 32 + 8 * fq;
;                     f32x4 r0, r1;
;                     if (MODE == 0) { r0 = *(const f32x4*)(src + col); r1 = *(const f32x4*)(src + col + 4); }
;                     else { const u32x4 w = *(const u32x4*)(xb + (size_t)row * D + col); r0 = (f32x4){bflo(w.x), bfhi(w.x), bflo(w.y), bfhi(w.y)}; r1 = (f32x4){bflo(w.z), bfhi(w.z), bflo(w.w), bfhi(w.w)}; }
;                     const f32x4 v0 = acc[ai][bj][m][0] + r0, v1 = acc[ai][bj][m][1] + r1;
;                     *(u32x4*)(xb + (size_t)row * D + col) = pack8(v0, v1);
;                     if (MODE != 2) {
;                         ss += ((v0[0] * v0[0] + v0[1] * v0[1]) + (v0[2] * v0[2] + v0[3] * v0[3])) + ((v1[0] * v1[0] + v1[1] * v1[1]) + (v1[2] * v1[2] + v1[3] * v1[3])); } }
;                 if (MODE != 2) { ss += __shfl_xor(ss, 16); ss += __shfl_xor(ss, 32);
;                     if (fq == 0) part[(size_t)row * 16 + u.pn * 4 + wc] = ss; }
.LBB0_1238:
	s_or_b64 exec, exec, s[30:31]
	v_add_u32_e32 v152, 0x80, v150
	v_ashrrev_i32_e32 v153, 31, v152
	s_waitcnt lgkmcnt(0)
	v_lshlrev_b64 v[170:171], 11, v[152:153]
	v_lshl_add_u64 v[170:171], s[88:89], 0, v[170:171]
	v_lshl_add_u64 v[178:179], v[148:149], 1, v[170:171]
	s_waitcnt vmcnt(14)
	v_lshlrev_b32_e32 v180, 16, v196
	v_and_b32_e32 v181, 0xffff0000, v196
	v_lshlrev_b32_e32 v170, 16, v197
	v_and_b32_e32 v171, 0xffff0000, v197
	v_lshlrev_b32_e32 v182, 16, v198
	v_and_b32_e32 v183, 0xffff0000, v198
	v_lshlrev_b32_e32 v172, 16, v199
	v_and_b32_e32 v173, 0xffff0000, v199
	v_lshlrev_b32_e32 v184, 16, v200
	v_and_b32_e32 v185, 0xffff0000, v200
	v_lshlrev_b32_e32 v174, 16, v201
	v_and_b32_e32 v175, 0xffff0000, v201
	v_lshlrev_b32_e32 v186, 16, v202
	v_and_b32_e32 v187, 0xffff0000, v202
	v_lshlrev_b32_e32 v176, 16, v203
	v_and_b32_e32 v177, 0xffff0000, v203
	v_pk_add_f32 v[188:189], v[64:65], v[170:171]
	v_pk_add_f32 v[180:181], v[62:63], v[180:181]
	v_pk_add_f32 v[190:191], v[60:61], v[172:173]
	v_pk_add_f32 v[172:173], v[58:59], v[182:183]
	v_pk_add_f32 v[174:175], v[48:49], v[174:175]
	v_pk_add_f32 v[182:183], v[46:47], v[184:185]
	v_pk_add_f32 v[176:177], v[44:45], v[176:177]
	v_pk_add_f32 v[184:185], v[42:43], v[186:187]
	v_cvt_pk_bf16_f32 v170, v180, v181
	v_cvt_pk_bf16_f32 v171, v188, v189
	v_mul_f32_e32 v151, v181, v181
	v_mul_f32_e32 v181, v189, v189
	v_mul_f32_e32 v186, v173, v173
	v_mul_f32_e32 v187, v191, v191
	v_mul_f32_e32 v189, v183, v183
	v_mul_f32_e32 v192, v175, v175
	v_mul_f32_e32 v193, v185, v185
	v_mul_f32_e32 v194, v177, v177
	v_fmac_f32_e32 v151, v180, v180
	v_fmac_f32_e32 v181, v188, v188
	v_fmac_f32_e32 v186, v172, v172
	v_fmac_f32_e32 v187, v190, v190
	v_fmac_f32_e32 v189, v182, v182
	v_fmac_f32_e32 v192, v174, v174
	v_fmac_f32_e32 v193, v184, v184
	v_fmac_f32_e32 v194, v176, v176
	v_add_f32_e32 v151, v151, v181
	v_add_f32_e32 v180, v186, v187
	v_add_f32_e32 v181, v189, v192
	v_add_f32_e32 v186, v193, v194
	v_add_f32_e32 v151, v151, v180
	v_add_f32_e32 v180, v181, v186
	v_add_f32_e32 v151, v151, v180
	ds_bpermute_b32 v180, v169, v151
	v_cvt_pk_bf16_f32 v172, v172, v173
	v_cvt_pk_bf16_f32 v173, v190, v191
	global_store_dwordx4 v[178:179], v[170:173], off
	s_waitcnt lgkmcnt(0)
	v_add_f32_e32 v151, v151, v180
	ds_bpermute_b32 v170, v168, v151
	v_cvt_pk_bf16_f32 v172, v182, v183
	v_cvt_pk_bf16_f32 v173, v174, v175
	v_cvt_pk_bf16_f32 v174, v184, v185
	v_cvt_pk_bf16_f32 v175, v176, v177
	global_store_dwordx4 v[178:179], v[172:175], off offset:256
	s_and_saveexec_b64 s[30:31], s[0:1]
	s_cbranch_execz .LBB0_1240
	s_lshl_b32 s34, s6, 2
	v_lshlrev_b64 v[152:153], 6, v[152:153]
	s_ashr_i32 s35, s34, 31
	v_lshl_add_u64 v[152:153], s[90:91], 0, v[152:153]
	v_lshl_add_u64 v[152:153], s[34:35], 2, v[152:153]
	s_lshl_b32 s34, s46, 2
	s_mov_b32 s35, s13
	s_waitcnt lgkmcnt(0)
	v_add_f32_e32 v151, v151, v170
	v_lshl_add_u64 v[152:153], v[152:153], 0, s[34:35]
	global_store_dword v[152:153], v151, off
.LBB0_1240:
	s_or_b64 exec, exec, s[30:31]
	v_add_u32_e32 v152, 0x90, v150
	v_ashrrev_i32_e32 v153, 31, v152
	s_waitcnt lgkmcnt(0)
	v_lshlrev_b64 v[170:171], 11, v[152:153]
	v_lshl_add_u64 v[170:171], s[88:89], 0, v[170:171]
	v_lshl_add_u64 v[178:179], v[148:149], 1, v[170:171]
	s_waitcnt vmcnt(14)
	v_lshlrev_b32_e32 v180, 16, v204
	v_and_b32_e32 v181, 0xffff0000, v204
	v_lshlrev_b32_e32 v170, 16, v205
	v_and_b32_e32 v171, 0xffff0000, v205
	v_lshlrev_b32_e32 v182, 16, v206
	v_and_b32_e32 v183, 0xffff0000, v206
	v_lshlrev_b32_e32 v172, 16, v207
	v_and_b32_e32 v173, 0xffff0000, v207
	v_lshlrev_b32_e32 v184, 16, v208
	v_and_b32_e32 v185, 0xffff0000, v208
	v_lshlrev_b32_e32 v174, 16, v209
	v_and_b32_e32 v175, 0xffff0000, v209
	v_lshlrev_b32_e32 v186, 16, v210
	v_and_b32_e32 v187, 0xffff0000, v210
	v_lshlrev_b32_e32 v176, 16, v211
	v_and_b32_e32 v177, 0xffff0000, v211
	v_pk_add_f32 v[188:189], v[56:57], v[170:171]
	v_pk_add_f32 v[180:181], v[54:55], v[180:181]
	v_pk_add_f32 v[190:191], v[52:53], v[172:173]
	v_pk_add_f32 v[172:173], v[50:51], v[182:183]
	v_pk_add_f32 v[174:175], v[32:33], v[174:175]
	v_pk_add_f32 v[182:183], v[30:31], v[184:185]
	v_pk_add_f32 v[176:177], v[28:29], v[176:177]
	v_pk_add_f32 v[184:185], v[26:27], v[186:187]
	v_cvt_pk_bf16_f32 v170, v180, v181
	v_cvt_pk_bf16_f32 v171, v188, v189
	v_mul_f32_e32 v151, v181, v181
	v_mul_f32_e32 v181, v189, v189
	v_mul_f32_e32 v186, v173, v173
	v_mul_f32_e32 v187, v191, v191
	v_mul_f32_e32 v189, v183, v183
	v_mul_f32_e32 v192, v175, v175
	v_mul_f32_e32 v193, v185, v185
	v_mul_f32_e32 v194, v177, v177
	v_fmac_f32_e32 v151, v180, v180
	v_fmac_f32_e32 v181, v188, v188
	v_fmac_f32_e32 v186, v172, v172
	v_fmac_f32_e32 v187, v190, v190
	v_fmac_f32_e32 v189, v182, v182
	v_fmac_f32_e32 v192, v174, v174
	v_fmac_f32_e32 v193, v184, v184
	v_fmac_f32_e32 v194, v176, v176
	v_add_f32_e32 v151, v151, v181
	v_add_f32_e32 v180, v186, v187
	v_add_f32_e32 v181, v189, v192
	v_add_f32_e32 v186, v193, v194
	v_add_f32_e32 v151, v151, v180
	v_add_f32_e32 v180, v181, v186
	v_add_f32_e32 v151, v151, v180
	ds_bpermute_b32 v180, v169, v151
	v_cvt_pk_bf16_f32 v172, v172, v173
	v_cvt_pk_bf16_f32 v173, v190, v191
	global_store_dwordx4 v[178:179], v[170:173], off
	s_waitcnt lgkmcnt(0)
	v_add_f32_e32 v151, v151, v180
	ds_bpermute_b32 v170, v168, v151
	v_cvt_pk_bf16_f32 v172, v182, v183
	v_cvt_pk_bf16_f32 v173, v174, v175
	v_cvt_pk_bf16_f32 v174, v184, v185
	v_cvt_pk_bf16_f32 v175, v176, v177
	global_store_dwordx4 v[178:179], v[172:175], off offset:256
	s_and_saveexec_b64 s[30:31], s[0:1]
	s_cbranch_execz .LBB0_1242
	s_lshl_b32 s34, s6, 2
	v_lshlrev_b64 v[152:153], 6, v[152:153]
	s_ashr_i32 s35, s34, 31
	v_lshl_add_u64 v[152:153], s[90:91], 0, v[152:153]
	v_lshl_add_u64 v[152:153], s[34:35], 2, v[152:153]
	s_lshl_b32 s34, s46, 2
	s_mov_b32 s35, s13
	s_waitcnt lgkmcnt(0)
	v_add_f32_e32 v151, v151, v170
	v_lshl_add_u64 v[152:153], v[152:153], 0, s[34:35]
	global_store_dword v[152:153], v151, off
; __device__ __forceinline__ u32x4 pack8(const f32x4 a, const f32x4 b) { u32x4 w; w.x = cvt_pk_bf16(a[0], a[1]); w.y = cvt_pk_bf16(a[2], a[3]); w.z = cvt_pk_bf16(b[0], b[1]); w.w = cvt_pk_bf16(b[2], b[3]); return w; }
;     __device__ __forceinline__ void operator()(const Acc& acc, const pg8::Unit& u, int wr, int wc, int fr, int fq) const {
;     ...
; #pragma unroll
;         for (int ai = 0; ai < 2; ++ai)
; #pragma unroll
;             for (int m = 0; m < 4; ++m) {
;                 const int row = u.pm * 256 + ai * 128 + wr * 64 + m * 16 + fr;
;                 const float* src = row < TP ? xp + (size_t)row * D : xs + (size_t)(row - TP) * D;
;                 float ss = 0.f;
; #pragma unroll
;                 for (int bj = 0; bj < 2; ++bj) { const int col = u.pn * 256 + bj * 128 + wc * 32 + 8 * fq;
;                     f32x4 r0, r1;
;                     if (MODE == 0) { r0 = *(const f32x4*)(src + col); r1 = *(const f32x4*)(src + col + 4); }
;                     else { const u32x4 w = *(const u32x4*)(xb + (size_t)row * D + col); r0 = (f32x4){bflo(w.x), bfhi(w.x), bflo(w.y), bfhi(w.y)}; r1 = (f32x4){bflo(w.z), bfhi(w.z), bflo(w.w), bfhi(w.w)}; }
;                     const f32x4 v0 = acc[ai][bj][m][0] + r0, v1 = acc[ai][bj][m][1] + r1;
;                     *(u32x4*)(xb + (size_t)row * D + col) = pack8(v0, v1);
;                     if (MODE != 2) {
;                         ss += ((v0[0] * v0[0] + v0[1] * v0[1]) + (v0[2] * v0[2] + v0[3] * v0[3])) + ((v1[0] * v1[0] + v1[1] * v1[1]) + (v1[2] * v1[2] + v1[3] * v1[3])); } }
;                 if (MODE != 2) { ss += __shfl_xor(ss, 16); ss += __shfl_xor(ss, 32);
;                     if (fq == 0) part[(size_t)row * 16 + u.pn * 4 + wc] = ss; }
.LBB0_1242:
	s_or_b64 exec, exec, s[30:31]
	v_add_u32_e32 v152, 0xa0, v150
	v_ashrrev_i32_e32 v153, 31, v152
	s_waitcnt lgkmcnt(0)
	v_lshlrev_b64 v[170:171], 11, v[152:153]
	v_lshl_add_u64 v[170:171], s[88:89], 0, v[170:171]
	v_lshl_add_u64 v[178:179], v[148:149], 1, v[170:171]
	s_waitcnt vmcnt(14)
	v_lshlrev_b32_e32 v180, 16, v212
	v_and_b32_e32 v181, 0xffff0000, v212
	v_lshlrev_b32_e32 v170, 16, v213
	v_and_b32_e32 v171, 0xffff0000, v213
	v_lshlrev_b32_e32 v182, 16, v214
	v_and_b32_e32 v183, 0xffff0000, v214
	v_lshlrev_b32_e32 v172, 16, v215
	v_and_b32_e32 v173, 0xffff0000, v215
	v_lshlrev_b32_e32 v184, 16, v216
	v_and_b32_e32 v185, 0xffff0000, v216
	v_lshlrev_b32_e32 v174, 16, v217
	v_and_b32_e32 v175, 0xffff0000, v217
	v_lshlrev_b32_e32 v186, 16, v218
	v_and_b32_e32 v187, 0xffff0000, v218
	v_lshlrev_b32_e32 v176, 16, v219
	v_and_b32_e32 v177, 0xffff0000, v219
	v_pk_add_f32 v[188:189], v[40:41], v[170:171]
	v_pk_add_f32 v[180:181], v[38:39], v[180:181]
	v_pk_add_f32 v[190:191], v[36:37], v[172:173]
	v_pk_add_f32 v[172:173], v[34:35], v[182:183]
	v_pk_add_f32 v[174:175], v[16:17], v[174:175]
	v_pk_add_f32 v[182:183], v[14:15], v[184:185]
	v_pk_add_f32 v[176:177], v[12:13], v[176:177]
	v_pk_add_f32 v[184:185], v[10:11], v[186:187]
	v_cvt_pk_bf16_f32 v170, v180, v181
	v_cvt_pk_bf16_f32 v171, v188, v189
	v_mul_f32_e32 v151, v181, v181
	v_mul_f32_e32 v181, v189, v189
	v_mul_f32_e32 v186, v173, v173
	v_mul_f32_e32 v187, v191, v191
	v_mul_f32_e32 v189, v183, v183
	v_mul_f32_e32 v192, v175, v175
	v_mul_f32_e32 v193, v185, v185
	v_mul_f32_e32 v194, v177, v177
	v_fmac_f32_e32 v151, v180, v180
	v_fmac_f32_e32 v181, v188, v188
	v_fmac_f32_e32 v186, v172, v172
	v_fmac_f32_e32 v187, v190, v190
	v_fmac_f32_e32 v189, v182, v182
	v_fmac_f32_e32 v192, v174, v174
	v_fmac_f32_e32 v193, v184, v184
	v_fmac_f32_e32 v194, v176, v176
	v_add_f32_e32 v151, v151, v181
	v_add_f32_e32 v180, v186, v187
	v_add_f32_e32 v181, v189, v192
	v_add_f32_e32 v186, v193, v194
	v_add_f32_e32 v151, v151, v180
	v_add_f32_e32 v180, v181, v186
	v_add_f32_e32 v151, v151, v180
	ds_bpermute_b32 v180, v169, v151
	v_cvt_pk_bf16_f32 v172, v172, v173
	v_cvt_pk_bf16_f32 v173, v190, v191
	global_store_dwordx4 v[178:179], v[170:173], off
	s_waitcnt lgkmcnt(0)
	v_add_f32_e32 v151, v151, v180
	ds_bpermute_b32 v170, v168, v151
	v_cvt_pk_bf16_f32 v172, v182, v183
	v_cvt_pk_bf16_f32 v173, v174, v175
	v_cvt_pk_bf16_f32 v174, v184, v185
	v_cvt_pk_bf16_f32 v175, v176, v177
	global_store_dwordx4 v[178:179], v[172:175], off offset:256
	s_and_saveexec_b64 s[30:31], s[0:1]
	s_cbranch_execz .LBB0_1244
	s_lshl_b32 s34, s6, 2
	v_lshlrev_b64 v[152:153], 6, v[152:153]
	s_ashr_i32 s35, s34, 31
	v_lshl_add_u64 v[152:153], s[90:91], 0, v[152:153]
	v_lshl_add_u64 v[152:153], s[34:35], 2, v[152:153]
	s_lshl_b32 s34, s46, 2
	s_mov_b32 s35, s13
	s_waitcnt lgkmcnt(0)
	v_add_f32_e32 v151, v151, v170
	v_lshl_add_u64 v[152:153], v[152:153], 0, s[34:35]
	global_store_dword v[152:153], v151, off
.LBB0_1244:
	s_or_b64 exec, exec, s[30:31]
	v_add_u32_e32 v150, 0xb0, v150
	v_ashrrev_i32_e32 v151, 31, v150
	v_lshlrev_b64 v[152:153], 11, v[150:151]
	v_lshl_add_u64 v[152:153], s[88:89], 0, v[152:153]
	v_lshl_add_u64 v[152:153], v[148:149], 1, v[152:153]
	s_waitcnt lgkmcnt(0)
	s_waitcnt vmcnt(14)
	v_lshlrev_b32_e32 v148, 16, v220
	v_and_b32_e32 v149, 0xffff0000, v220
	v_lshlrev_b32_e32 v170, 16, v221
	v_and_b32_e32 v171, 0xffff0000, v221
	v_lshlrev_b32_e32 v178, 16, v222
	v_and_b32_e32 v179, 0xffff0000, v222
	v_lshlrev_b32_e32 v172, 16, v223
	v_and_b32_e32 v173, 0xffff0000, v223
	v_lshlrev_b32_e32 v180, 16, v224
	v_and_b32_e32 v181, 0xffff0000, v224
	v_lshlrev_b32_e32 v174, 16, v225
	v_and_b32_e32 v175, 0xffff0000, v225
	v_lshlrev_b32_e32 v182, 16, v226
	v_and_b32_e32 v183, 0xffff0000, v226
	v_lshlrev_b32_e32 v176, 16, v227
	v_and_b32_e32 v177, 0xffff0000, v227
	v_pk_add_f32 v[184:185], v[24:25], v[170:171]
	v_pk_add_f32 v[148:149], v[22:23], v[148:149]
	v_pk_add_f32 v[186:187], v[20:21], v[172:173]
	v_pk_add_f32 v[172:173], v[18:19], v[178:179]
	v_pk_add_f32 v[174:175], v[8:9], v[174:175]
	v_pk_add_f32 v[178:179], v[6:7], v[180:181]
	v_pk_add_f32 v[176:177], v[4:5], v[176:177]
	v_pk_add_f32 v[180:181], v[2:3], v[182:183]
	v_cvt_pk_bf16_f32 v170, v148, v149
	v_cvt_pk_bf16_f32 v171, v184, v185
	v_mul_f32_e32 v149, v149, v149
	v_mul_f32_e32 v182, v185, v185
	v_mul_f32_e32 v183, v173, v173
	v_mul_f32_e32 v185, v187, v187
	v_mul_f32_e32 v188, v179, v179
	v_mul_f32_e32 v189, v175, v175
	v_mul_f32_e32 v190, v181, v181
	v_mul_f32_e32 v191, v177, v177
	v_fmac_f32_e32 v149, v148, v148
	v_fmac_f32_e32 v182, v184, v184
	v_fmac_f32_e32 v183, v172, v172
	v_fmac_f32_e32 v185, v186, v186
	v_fmac_f32_e32 v188, v178, v178
	v_fmac_f32_e32 v189, v174, v174
	v_fmac_f32_e32 v190, v180, v180
	v_fmac_f32_e32 v191, v176, v176
	v_add_f32_e32 v148, v149, v182
	v_add_f32_e32 v149, v183, v185
	v_add_f32_e32 v182, v188, v189
	v_add_f32_e32 v183, v190, v191
	v_add_f32_e32 v148, v148, v149
	v_add_f32_e32 v149, v182, v183
	v_add_f32_e32 v148, v148, v149
	ds_bpermute_b32 v149, v169, v148
	v_cvt_pk_bf16_f32 v172, v172, v173
	v_cvt_pk_bf16_f32 v173, v186, v187
	global_store_dwordx4 v[152:153], v[170:173], off
	s_waitcnt lgkmcnt(0)
	v_add_f32_e32 v148, v148, v149
	ds_bpermute_b32 v149, v168, v148
	v_cvt_pk_bf16_f32 v170, v178, v179
	v_cvt_pk_bf16_f32 v171, v174, v175
	v_cvt_pk_bf16_f32 v172, v180, v181
	v_cvt_pk_bf16_f32 v173, v176, v177
	global_store_dwordx4 v[152:153], v[170:173], off offset:256
	s_and_saveexec_b64 s[30:31], s[0:1]
	s_cbranch_execz .LBB0_1246
	s_waitcnt lgkmcnt(0)
	v_add_f32_e32 v152, v148, v149
	s_lshl_b32 s34, s6, 2
	v_lshlrev_b64 v[148:149], 6, v[150:151]
	s_ashr_i32 s35, s34, 31
	v_lshl_add_u64 v[148:149], s[90:91], 0, v[148:149]
	v_lshl_add_u64 v[148:149], s[34:35], 2, v[148:149]
	s_lshl_b32 s34, s46, 2
	s_mov_b32 s35, s13
	v_lshl_add_u64 v[148:149], v[148:149], 0, s[34:35]
	global_store_dword v[148:149], v152, off
